# baseline (speedup 1.0000x reference)
; DEVINL u16 f2bf(float f) { uint32_t u = __float_as_uint(f); u += 0x7FFFu + ((u >> 16) & 1u); return (u16)(u >> 16); }
; DEVINL float bfs2f(short h) { return __uint_as_float(((uint32_t)(u16)h) << 16); }
; DEVINL void phase_conv(const Params& p, int layer, int wv) {
;     ...
; #pragma unroll 8
;       for (int i = 0; i < 32; ++i) {
;         const bf16x8 r3 = *(const bf16x8*)(src + (size_t)i * HS);
;         bf16x8 o;
; #pragma unroll
;         for (int e = 0; e < 8; ++e) {
;           float v = bias[e] + w[0][e] * bfs2f(r0[e]) + w[1][e] * bfs2f(r1[e]) + w[2][e] * bfs2f(r2[e]) + w[3][e] * bfs2f(r3[e]);
;           v = v / (1.f + __expf(-v));
;           o[e] = (short)f2bf(v);
;         }
;         *(bf16x8*)(xc + (size_t)(tokA + i) * 1536 + ch0) = o;
;         r0 = r1; r1 = r2; r2 = r3;
.LBB0_454:
	v_add_co_u32_e32 v62, vcc, 0xfffef000, v42
	s_waitcnt vmcnt(0)
	v_and_b32_e32 v75, 0xffff0000, v214
	v_addc_co_u32_e32 v63, vcc, -1, v43, vcc
	global_load_dwordx4 v[192:195], v[62:63], off offset:-2048
	v_lshlrev_b32_e32 v74, 16, v214
	v_add_co_u32_e64 v46, s[0:1], s31, v42
	v_and_b32_e32 v81, 0xffff0000, v215
	v_lshlrev_b32_e32 v80, 16, v215
	v_addc_co_u32_e64 v47, s[0:1], -1, v43, s[0:1]
	v_and_b32_e32 v69, 0xffff0000, v212
	v_lshlrev_b32_e32 v68, 16, v212
	v_and_b32_e32 v65, 0xffff0000, v220
	v_lshlrev_b32_e32 v64, 16, v220
	v_and_b32_e32 v73, 0xffff0000, v213
	v_lshlrev_b32_e32 v72, 16, v213
	v_and_b32_e32 v45, 0xffff0000, v221
	v_lshlrev_b32_e32 v44, 16, v221
	v_and_b32_e32 v53, 0xffff0000, v218
	v_lshlrev_b32_e32 v52, 16, v218
	v_add_co_u32_e64 v50, s[0:1], s33, v42
	v_and_b32_e32 v79, 0xffff0000, v219
	v_lshlrev_b32_e32 v78, 16, v219
	v_addc_co_u32_e64 v51, s[0:1], -1, v43, s[0:1]
	v_and_b32_e32 v67, 0xffff0000, v216
	v_lshlrev_b32_e32 v66, 16, v216
	v_and_b32_e32 v71, 0xffff0000, v217
	v_lshlrev_b32_e32 v70, 16, v217
	v_and_b32_e32 v49, 0xffff0000, v222
	v_lshlrev_b32_e32 v48, 16, v222
	v_add_co_u32_e64 v54, s[0:1], s34, v42
	v_and_b32_e32 v77, 0xffff0000, v223
	v_lshlrev_b32_e32 v76, 16, v223
	v_addc_co_u32_e64 v55, s[0:1], -1, v43, s[0:1]
	v_add_co_u32_e64 v82, s[0:1], s25, v42
	v_pk_fma_f32 v[68:69], v[4:5], v[68:69], v[36:37]
	s_nop 0
	v_addc_co_u32_e64 v83, s[0:1], -1, v43, s[0:1]
	v_add_co_u32_e64 v84, s[0:1], s26, v42
	v_pk_fma_f32 v[80:81], v[2:3], v[80:81], v[34:35]
	s_nop 0
	v_addc_co_u32_e64 v85, s[0:1], -1, v43, s[0:1]
	v_pk_fma_f32 v[96:97], v[4:5], v[66:67], v[36:37]
	v_pk_fma_f32 v[98:99], v[6:7], v[70:71], v[38:39]
	v_pk_fma_f32 v[100:101], v[0:1], v[52:53], v[32:33]
	v_pk_fma_f32 v[102:103], v[2:3], v[78:79], v[34:35]
	v_pk_fma_f32 v[112:113], v[8:9], v[66:67], v[68:69]
	v_pk_fma_f32 v[78:79], v[18:19], v[78:79], v[80:81]
	v_add_u32_e32 v41, s36, v89
	v_add_co_u32_e64 v86, s[0:1], s27, v42
	v_pk_fma_f32 v[72:73], v[6:7], v[72:73], v[38:39]
	v_pk_fma_f32 v[104:105], v[4:5], v[64:65], v[36:37]
	v_pk_fma_f32 v[110:111], v[2:3], v[76:77], v[34:35]
	v_pk_fma_f32 v[80:81], v[8:9], v[64:65], v[96:97]
	v_pk_fma_f32 v[96:97], v[10:11], v[44:45], v[98:99]
	v_pk_fma_f32 v[98:99], v[16:17], v[48:49], v[100:101]
	v_pk_fma_f32 v[100:101], v[18:19], v[76:77], v[102:103]
	v_pk_fma_f32 v[64:65], v[12:13], v[64:65], v[112:113]
	v_pk_fma_f32 v[76:77], v[22:23], v[76:77], v[78:79]
	v_addc_co_u32_e64 v87, s[0:1], -1, v43, s[0:1]
	global_load_dwordx4 v[196:199], v[46:47], off
	global_load_dwordx4 v[200:203], v[50:51], off offset:-2048
	global_load_dwordx4 v[204:207], v[54:55], off
	global_load_dwordx4 v[208:211], v[82:83], off offset:-2048
	global_load_dwordx4 v[212:215], v[84:85], off
	global_load_dwordx4 v[216:219], v[86:87], off offset:-2048
	global_load_dwordx4 v[220:223], v[42:43], off
	v_mad_i64_i32 v[164:165], s[0:1], v41, s30, v[58:59]
	v_add_u32_e32 v118, 1, v41
	v_add_u32_e32 v119, 2, v41
	v_add_u32_e32 v120, 3, v41
	v_add_u32_e32 v121, 4, v41
	v_add_u32_e32 v122, 5, v41
	v_add_u32_e32 v123, 6, v41
	v_add_u32_e32 v41, 7, v41
	v_pk_fma_f32 v[114:115], v[10:11], v[70:71], v[72:73]
	v_pk_fma_f32 v[74:75], v[0:1], v[74:75], v[32:33]
	v_pk_fma_f32 v[106:107], v[6:7], v[44:45], v[38:39]
	v_mad_i64_i32 v[180:181], s[0:1], v41, s30, v[58:59]
	s_waitcnt vmcnt(0)
	v_and_b32_e32 v79, 0xffff0000, v192
	v_lshlrev_b32_e32 v78, 16, v192
	v_and_b32_e32 v113, 0xffff0000, v195
	v_lshlrev_b32_e32 v112, 16, v195
	v_pk_fma_f32 v[64:65], v[24:25], v[78:79], v[64:65]
	v_pk_fma_f32 v[44:45], v[14:15], v[44:45], v[114:115]
	v_and_b32_e32 v103, 0xffff0000, v193
	v_lshlrev_b32_e32 v102, 16, v193
	v_and_b32_e32 v91, 0xffff0000, v194
	v_lshlrev_b32_e32 v90, 16, v194
	v_pk_fma_f32 v[92:93], v[30:31], v[112:113], v[76:77]
	v_mul_f32_e32 v41, 0xbfb8aa3b, v64
	v_mul_f32_e32 v77, 0xbfb8aa3b, v65
	v_pk_fma_f32 v[116:117], v[16:17], v[52:53], v[74:75]
	v_pk_fma_f32 v[44:45], v[26:27], v[102:103], v[44:45]
	v_exp_f32_e32 v76, v41
	v_exp_f32_e32 v77, v77
	v_pk_fma_f32 v[108:109], v[0:1], v[48:49], v[32:33]
	v_pk_fma_f32 v[48:49], v[20:21], v[48:49], v[116:117]
	v_pk_fma_f32 v[80:81], v[12:13], v[78:79], v[80:81]
	v_pk_fma_f32 v[104:105], v[8:9], v[78:79], v[104:105]
	v_pk_fma_f32 v[114:115], v[4:5], v[78:79], v[36:37]
	v_mul_f32_e32 v78, 0xbfb8aa3b, v44
	v_mul_f32_e32 v79, 0xbfb8aa3b, v45
	v_pk_fma_f32 v[48:49], v[28:29], v[90:91], v[48:49]
	v_exp_f32_e32 v78, v78
	v_exp_f32_e32 v79, v79
	v_mul_f32_e32 v116, 0xbfb8aa3b, v48
	v_mul_f32_e32 v117, 0xbfb8aa3b, v49
	v_exp_f32_e32 v116, v116
	v_exp_f32_e32 v117, v117
	v_pk_add_f32 v[76:77], v[76:77], 1.0 op_sel_hi:[1,0]
	v_mad_i64_i32 v[166:167], s[0:1], v118, s30, v[58:59]
	v_mad_i64_i32 v[168:169], s[0:1], v119, s30, v[58:59]
	v_mul_f32_e32 v118, 0xbfb8aa3b, v92
	v_mul_f32_e32 v119, 0xbfb8aa3b, v93
	v_mad_i64_i32 v[172:173], s[0:1], v121, s30, v[58:59]
	v_exp_f32_e32 v118, v118
	v_exp_f32_e32 v119, v119
	v_pk_add_f32 v[78:79], v[78:79], 1.0 op_sel_hi:[1,0]
	v_rcp_f32_e32 v135, v76
	v_mad_i64_i32 v[178:179], s[0:1], v123, s30, v[58:59]
	v_rcp_f32_e32 v136, v77
	v_pk_add_f32 v[116:117], v[116:117], 1.0 op_sel_hi:[1,0]
	v_rcp_f32_e32 v137, v78
	v_rcp_f32_e32 v138, v79
	v_pk_add_f32 v[118:119], v[118:119], 1.0 op_sel_hi:[1,0]
	v_rcp_f32_e32 v139, v116
	v_mad_i64_i32 v[170:171], s[0:1], v120, s30, v[58:59]
	v_mad_i64_i32 v[174:175], s[0:1], v122, s30, v[58:59]
	v_rcp_f32_e32 v140, v117
	v_rcp_f32_e32 v141, v118
	v_rcp_f32_e32 v142, v119
	v_mul_f32_e32 v41, v64, v135
	s_mov_b64 vcc, s[0:1]
	v_mul_f32_e32 v64, v65, v136
	s_mov_b64 vcc, s[2:3]
	v_mul_f32_e32 v65, v44, v137
	s_mov_b64 vcc, s[4:5]
	v_mov_b32_e32 v44, v65
; DEVINL u16 f2bf(float f) { uint32_t u = __float_as_uint(f); u += 0x7FFFu + ((u >> 16) & 1u); return (u16)(u >> 16); }
; DEVINL float bfs2f(short h) { return __uint_as_float(((uint32_t)(u16)h) << 16); }
; DEVINL void phase_conv(const Params& p, int layer, int wv) {
;     ...
; #pragma unroll 8
;       for (int i = 0; i < 32; ++i) {
;         const bf16x8 r3 = *(const bf16x8*)(src + (size_t)i * HS);
;         bf16x8 o;
; #pragma unroll
;         for (int e = 0; e < 8; ++e) {
;           float v = bias[e] + w[0][e] * bfs2f(r0[e]) + w[1][e] * bfs2f(r1[e]) + w[2][e] * bfs2f(r2[e]) + w[3][e] * bfs2f(r3[e]);
;           v = v / (1.f + __expf(-v));
;           o[e] = (short)f2bf(v);
;         }
;         *(bf16x8*)(xc + (size_t)(tokA + i) * 1536 + ch0) = o;
;         r0 = r1; r1 = r2; r2 = r3;
	v_mul_f32_e32 v65, v45, v138
	s_mov_b64 vcc, s[6:7]
	v_bfe_u32 v76, v41, 16, 1
	v_bfe_u32 v77, v64, 16, 1
	v_mov_b32_e32 v45, v65
	v_mul_f32_e32 v65, v48, v139
	s_mov_b64 vcc, s[8:9]
	v_add3_u32 v41, v41, v76, s28
	v_bfe_u32 v76, v44, 16, 1
	v_add3_u32 v64, v64, v77, s28
	v_mov_b32_e32 v48, v65
	v_mul_f32_e32 v65, v49, v140
	s_mov_b64 vcc, s[10:11]
	v_bfe_u32 v77, v45, 16, 1
	v_add3_u32 v44, v44, v76, s28
	v_perm_b32 v224, v64, v41, s29
	v_mov_b32_e32 v41, v65
	v_mul_f32_e32 v49, v92, v141
	s_mov_b64 vcc, s[12:13]
	v_add3_u32 v45, v45, v77, s28
	v_mul_f32_e32 v65, v93, v142
	v_bfe_u32 v64, v48, 16, 1
	v_bfe_u32 v78, v41, 16, 1
	v_perm_b32 v225, v45, v44, s29
	v_mov_b32_e32 v44, v65
	v_add3_u32 v48, v48, v64, s28
	v_bfe_u32 v45, v49, 16, 1
	v_add3_u32 v41, v41, v78, s28
	v_bfe_u32 v64, v44, 16, 1
	v_add3_u32 v45, v49, v45, s28
	v_perm_b32 v226, v41, v48, s29
	v_add3_u32 v41, v44, v64, s28
	v_perm_b32 v227, v41, v45, s29
	global_store_dwordx4 v[164:165], v[224:227], off
	v_pk_fma_f32 v[98:99], v[20:21], v[90:91], v[98:99]
	v_pk_fma_f32 v[108:109], v[16:17], v[90:91], v[108:109]
	v_pk_fma_f32 v[90:91], v[0:1], v[90:91], v[32:33]
	v_pk_fma_f32 v[96:97], v[14:15], v[102:103], v[96:97]
	v_pk_fma_f32 v[100:101], v[22:23], v[112:113], v[100:101]
	v_pk_fma_f32 v[110:111], v[18:19], v[112:113], v[110:111]
	v_pk_fma_f32 v[106:107], v[10:11], v[102:103], v[106:107]
	v_pk_fma_f32 v[112:113], v[2:3], v[112:113], v[34:35]
	v_pk_fma_f32 v[102:103], v[6:7], v[102:103], v[38:39]
	s_add_i32 s36, s36, 8
	s_cmp_eq_u32 s36, 32
	v_and_b32_e32 v49, 0xffff0000, v196
	v_lshlrev_b32_e32 v48, 16, v196
	v_and_b32_e32 v65, 0xffff0000, v197
	v_lshlrev_b32_e32 v64, 16, v197
	v_and_b32_e32 v45, 0xffff0000, v198
	v_lshlrev_b32_e32 v44, 16, v198
	v_and_b32_e32 v77, 0xffff0000, v199
	v_lshlrev_b32_e32 v76, 16, v199
	v_pk_fma_f32 v[46:47], v[24:25], v[48:49], v[80:81]
	v_pk_fma_f32 v[80:81], v[28:29], v[44:45], v[98:99]
	v_pk_fma_f32 v[98:99], v[20:21], v[44:45], v[108:109]
	v_pk_fma_f32 v[90:91], v[16:17], v[44:45], v[90:91]
	v_pk_fma_f32 v[108:109], v[0:1], v[44:45], v[32:33]
	v_mul_f32_e32 v41, 0xbfb8aa3b, v46
	v_mul_f32_e32 v45, 0xbfb8aa3b, v47
	v_pk_fma_f32 v[78:79], v[26:27], v[64:65], v[96:97]
	v_exp_f32_e32 v44, v41
	v_exp_f32_e32 v45, v45
	v_pk_fma_f32 v[92:93], v[30:31], v[76:77], v[100:101]
	v_pk_fma_f32 v[100:101], v[22:23], v[76:77], v[110:111]
	v_mul_f32_e32 v110, 0xbfb8aa3b, v78
	v_mul_f32_e32 v111, 0xbfb8aa3b, v79
	v_exp_f32_e32 v110, v110
	v_exp_f32_e32 v111, v111
	v_pk_fma_f32 v[96:97], v[14:15], v[64:65], v[106:107]
	v_pk_fma_f32 v[106:107], v[18:19], v[76:77], v[112:113]
	v_mul_f32_e32 v112, 0xbfb8aa3b, v80
	v_mul_f32_e32 v113, 0xbfb8aa3b, v81
	v_exp_f32_e32 v112, v112
	v_exp_f32_e32 v113, v113
	v_pk_add_f32 v[44:45], v[44:45], 1.0 op_sel_hi:[1,0]
	v_pk_fma_f32 v[94:95], v[12:13], v[48:49], v[104:105]
	v_pk_fma_f32 v[104:105], v[8:9], v[48:49], v[114:115]
	v_mul_f32_e32 v114, 0xbfb8aa3b, v92
	v_mul_f32_e32 v115, 0xbfb8aa3b, v93
	v_exp_f32_e32 v114, v114
	v_exp_f32_e32 v115, v115
	v_pk_add_f32 v[110:111], v[110:111], 1.0 op_sel_hi:[1,0]
	v_rcp_f32_e32 v131, v44
	v_rcp_f32_e32 v132, v45
	v_pk_add_f32 v[112:113], v[112:113], 1.0 op_sel_hi:[1,0]
	v_rcp_f32_e32 v133, v110
	v_rcp_f32_e32 v134, v111
	v_pk_add_f32 v[114:115], v[114:115], 1.0 op_sel_hi:[1,0]
	v_rcp_f32_e32 v135, v112
	v_rcp_f32_e32 v136, v113
	v_rcp_f32_e32 v137, v114
	v_rcp_f32_e32 v138, v115
	v_mul_f32_e32 v41, v46, v131
	s_mov_b64 vcc, s[0:1]
	v_mul_f32_e32 v44, v47, v132
	s_mov_b64 vcc, s[2:3]
	v_mul_f32_e32 v45, v78, v133
	s_mov_b64 vcc, s[4:5]
	v_bfe_u32 v46, v41, 16, 1
	v_mul_f32_e32 v47, v79, v134
	s_mov_b64 vcc, s[6:7]
	v_bfe_u32 v78, v44, 16, 1
	v_add3_u32 v41, v41, v46, s28
	v_mov_b32_e32 v46, v47
	v_mul_f32_e32 v47, v80, v135
	s_mov_b64 vcc, s[8:9]
	v_add3_u32 v44, v44, v78, s28
	v_mul_f32_e32 v78, v81, v136
	s_mov_b64 vcc, s[10:11]
	v_bfe_u32 v79, v45, 16, 1
	v_bfe_u32 v80, v46, 16, 1
	v_perm_b32 v228, v44, v41, s29
	v_mov_b32_e32 v41, v78
	v_mul_f32_e32 v78, v92, v137
	s_mov_b64 vcc, s[12:13]
	v_add3_u32 v45, v45, v79, s28
	v_bfe_u32 v79, v47, 16, 1
	v_add3_u32 v46, v46, v80, s28
	v_mul_f32_e32 v80, v93, v138
	v_bfe_u32 v81, v41, 16, 1
	v_add3_u32 v47, v47, v79, s28
	v_mov_b32_e32 v79, v80
	v_perm_b32 v229, v46, v45, s29
	v_bfe_u32 v46, v78, 16, 1
	v_add3_u32 v41, v41, v81, s28
	v_bfe_u32 v80, v79, 16, 1
	v_add3_u32 v78, v78, v46, s28
	v_perm_b32 v230, v41, v47, s29
	v_add3_u32 v41, v79, v80, s28
	v_perm_b32 v231, v41, v78, s29
	global_store_dwordx4 v[166:167], v[228:231], off
	v_pk_fma_f32 v[102:103], v[10:11], v[64:65], v[102:103]
	v_pk_fma_f32 v[48:49], v[4:5], v[48:49], v[36:37]
	v_pk_fma_f32 v[64:65], v[6:7], v[64:65], v[38:39]
	v_pk_fma_f32 v[76:77], v[2:3], v[76:77], v[34:35]
	v_and_b32_e32 v51, 0xffff0000, v200
	v_lshlrev_b32_e32 v50, 16, v200
	v_and_b32_e32 v75, 0xffff0000, v201
	v_lshlrev_b32_e32 v74, 16, v201
	v_and_b32_e32 v45, 0xffff0000, v202
	v_lshlrev_b32_e32 v44, 16, v202
	v_and_b32_e32 v79, 0xffff0000, v203
	v_lshlrev_b32_e32 v78, 16, v203
	v_pk_fma_f32 v[46:47], v[24:25], v[50:51], v[94:95]
	v_pk_fma_f32 v[80:81], v[26:27], v[74:75], v[96:97]
	v_pk_fma_f32 v[92:93], v[28:29], v[44:45], v[98:99]
	v_pk_fma_f32 v[96:97], v[12:13], v[50:51], v[104:105]
	v_pk_fma_f32 v[98:99], v[14:15], v[74:75], v[102:103]
	v_pk_fma_f32 v[90:91], v[20:21], v[44:45], v[90:91]
	v_pk_fma_f32 v[102:103], v[16:17], v[44:45], v[108:109]
	v_pk_fma_f32 v[104:105], v[0:1], v[44:45], v[32:33]
	v_mul_f32_e32 v41, 0xbfb8aa3b, v46
	v_mul_f32_e32 v45, 0xbfb8aa3b, v47
	v_exp_f32_e32 v44, v41
	v_exp_f32_e32 v45, v45
	v_pk_fma_f32 v[94:95], v[30:31], v[78:79], v[100:101]
; DEVINL u16 f2bf(float f) { uint32_t u = __float_as_uint(f); u += 0x7FFFu + ((u >> 16) & 1u); return (u16)(u >> 16); }
; DEVINL float bfs2f(short h) { return __uint_as_float(((uint32_t)(u16)h) << 16); }
; DEVINL void phase_conv(const Params& p, int layer, int wv) {
;     ...
; #pragma unroll 8
;       for (int i = 0; i < 32; ++i) {
;         const bf16x8 r3 = *(const bf16x8*)(src + (size_t)i * HS);
;         bf16x8 o;
; #pragma unroll
;         for (int e = 0; e < 8; ++e) {
;           float v = bias[e] + w[0][e] * bfs2f(r0[e]) + w[1][e] * bfs2f(r1[e]) + w[2][e] * bfs2f(r2[e]) + w[3][e] * bfs2f(r3[e]);
;           v = v / (1.f + __expf(-v));
;           o[e] = (short)f2bf(v);
;         }
;         *(bf16x8*)(xc + (size_t)(tokA + i) * 1536 + ch0) = o;
;         r0 = r1; r1 = r2; r2 = r3;
;       }
	v_pk_fma_f32 v[100:101], v[22:23], v[78:79], v[106:107]
	v_mul_f32_e32 v106, 0xbfb8aa3b, v80
	v_mul_f32_e32 v107, 0xbfb8aa3b, v81
	v_exp_f32_e32 v106, v106
	v_exp_f32_e32 v107, v107
	v_mul_f32_e32 v108, 0xbfb8aa3b, v92
	v_mul_f32_e32 v109, 0xbfb8aa3b, v93
	v_exp_f32_e32 v108, v108
	v_exp_f32_e32 v109, v109
	v_pk_add_f32 v[44:45], v[44:45], 1.0 op_sel_hi:[1,0]
	v_mul_f32_e32 v110, 0xbfb8aa3b, v94
	v_mul_f32_e32 v111, 0xbfb8aa3b, v95
	v_exp_f32_e32 v110, v110
	v_exp_f32_e32 v111, v111
	v_pk_add_f32 v[106:107], v[106:107], 1.0 op_sel_hi:[1,0]
	v_rcp_f32_e32 v127, v44
	v_rcp_f32_e32 v128, v45
	v_pk_add_f32 v[108:109], v[108:109], 1.0 op_sel_hi:[1,0]
	v_rcp_f32_e32 v129, v106
	v_rcp_f32_e32 v130, v107
	v_pk_add_f32 v[110:111], v[110:111], 1.0 op_sel_hi:[1,0]
	v_rcp_f32_e32 v131, v108
	v_rcp_f32_e32 v132, v109
	v_rcp_f32_e32 v133, v110
	v_rcp_f32_e32 v134, v111
	v_mul_f32_e32 v41, v46, v127
	s_mov_b64 vcc, s[0:1]
	v_mul_f32_e32 v44, v47, v128
	s_mov_b64 vcc, s[2:3]
	v_mul_f32_e32 v45, v80, v129
	s_mov_b64 vcc, s[4:5]
	v_bfe_u32 v46, v41, 16, 1
	v_mul_f32_e32 v47, v81, v130
	s_mov_b64 vcc, s[6:7]
	v_bfe_u32 v80, v44, 16, 1
	v_add3_u32 v41, v41, v46, s28
	v_mov_b32_e32 v46, v47
	v_mul_f32_e32 v47, v92, v131
	s_mov_b64 vcc, s[8:9]
	v_add3_u32 v44, v44, v80, s28
	v_mul_f32_e32 v80, v93, v132
	s_mov_b64 vcc, s[10:11]
	v_bfe_u32 v81, v45, 16, 1
	v_bfe_u32 v92, v46, 16, 1
	v_perm_b32 v232, v44, v41, s29
	v_mov_b32_e32 v41, v80
	v_mul_f32_e32 v80, v94, v133
	s_mov_b64 vcc, s[12:13]
	v_add3_u32 v45, v45, v81, s28
	v_bfe_u32 v81, v47, 16, 1
	v_add3_u32 v46, v46, v92, s28
	v_mul_f32_e32 v92, v95, v134
	v_bfe_u32 v93, v41, 16, 1
	v_add3_u32 v47, v47, v81, s28
	v_mov_b32_e32 v81, v92
	v_perm_b32 v233, v46, v45, s29
	v_bfe_u32 v46, v80, 16, 1
	v_add3_u32 v41, v41, v93, s28
	v_bfe_u32 v92, v81, 16, 1
	v_add3_u32 v80, v80, v46, s28
	v_perm_b32 v234, v41, v47, s29
	v_add3_u32 v41, v81, v92, s28
	v_perm_b32 v235, v41, v80, s29
	global_store_dwordx4 v[168:169], v[232:235], off
	v_pk_fma_f32 v[48:49], v[8:9], v[50:51], v[48:49]
	v_pk_fma_f32 v[64:65], v[10:11], v[74:75], v[64:65]
	v_pk_fma_f32 v[76:77], v[18:19], v[78:79], v[76:77]
	v_pk_fma_f32 v[50:51], v[4:5], v[50:51], v[36:37]
	v_pk_fma_f32 v[74:75], v[6:7], v[74:75], v[38:39]
	v_pk_fma_f32 v[78:79], v[2:3], v[78:79], v[34:35]
	v_and_b32_e32 v55, 0xffff0000, v204
	v_lshlrev_b32_e32 v54, 16, v204
	v_and_b32_e32 v73, 0xffff0000, v205
	v_lshlrev_b32_e32 v72, 16, v205
	v_and_b32_e32 v45, 0xffff0000, v206
	v_lshlrev_b32_e32 v44, 16, v206
	v_and_b32_e32 v81, 0xffff0000, v207
	v_lshlrev_b32_e32 v80, 16, v207
	v_pk_fma_f32 v[46:47], v[24:25], v[54:55], v[96:97]
	v_pk_fma_f32 v[92:93], v[26:27], v[72:73], v[98:99]
	v_pk_fma_f32 v[90:91], v[28:29], v[44:45], v[90:91]
	v_pk_fma_f32 v[94:95], v[30:31], v[80:81], v[100:101]
	v_pk_fma_f32 v[96:97], v[20:21], v[44:45], v[102:103]
	v_pk_fma_f32 v[98:99], v[16:17], v[44:45], v[104:105]
	v_pk_fma_f32 v[100:101], v[0:1], v[44:45], v[32:33]
	v_mul_f32_e32 v41, 0xbfb8aa3b, v46
	v_mul_f32_e32 v45, 0xbfb8aa3b, v47
	v_exp_f32_e32 v44, v41
	v_exp_f32_e32 v45, v45
	v_mul_f32_e32 v102, 0xbfb8aa3b, v92
	v_mul_f32_e32 v103, 0xbfb8aa3b, v93
	v_exp_f32_e32 v102, v102
	v_exp_f32_e32 v103, v103
	v_mul_f32_e32 v104, 0xbfb8aa3b, v90
	v_mul_f32_e32 v105, 0xbfb8aa3b, v91
	v_exp_f32_e32 v104, v104
	v_exp_f32_e32 v105, v105
	v_pk_add_f32 v[44:45], v[44:45], 1.0 op_sel_hi:[1,0]
	v_mul_f32_e32 v106, 0xbfb8aa3b, v94
	v_mul_f32_e32 v107, 0xbfb8aa3b, v95
	v_exp_f32_e32 v106, v106
	v_exp_f32_e32 v107, v107
	v_pk_add_f32 v[102:103], v[102:103], 1.0 op_sel_hi:[1,0]
	v_rcp_f32_e32 v123, v44
	v_rcp_f32_e32 v124, v45
	v_pk_add_f32 v[104:105], v[104:105], 1.0 op_sel_hi:[1,0]
	v_rcp_f32_e32 v125, v102
	v_rcp_f32_e32 v126, v103
	v_pk_add_f32 v[106:107], v[106:107], 1.0 op_sel_hi:[1,0]
	v_rcp_f32_e32 v127, v104
	v_rcp_f32_e32 v128, v105
	v_rcp_f32_e32 v129, v106
	v_rcp_f32_e32 v130, v107
	v_mul_f32_e32 v41, v46, v123
	s_mov_b64 vcc, s[0:1]
	v_mul_f32_e32 v44, v47, v124
	s_mov_b64 vcc, s[2:3]
	v_mul_f32_e32 v45, v92, v125
	s_mov_b64 vcc, s[4:5]
	v_bfe_u32 v46, v41, 16, 1
	v_mul_f32_e32 v47, v93, v126
	s_mov_b64 vcc, s[6:7]
	v_bfe_u32 v92, v44, 16, 1
	v_add3_u32 v41, v41, v46, s28
	v_mov_b32_e32 v46, v47
	v_mul_f32_e32 v47, v90, v127
	s_mov_b64 vcc, s[8:9]
	v_add3_u32 v44, v44, v92, s28
	v_mul_f32_e32 v90, v91, v128
	s_mov_b64 vcc, s[10:11]
	v_bfe_u32 v92, v46, 16, 1
	v_perm_b32 v236, v44, v41, s29
	v_mov_b32_e32 v41, v90
	v_mul_f32_e32 v90, v94, v129
	s_mov_b64 vcc, s[12:13]
	v_bfe_u32 v93, v45, 16, 1
	v_bfe_u32 v91, v47, 16, 1
	v_add3_u32 v46, v46, v92, s28
	v_mul_f32_e32 v92, v95, v130
	v_add3_u32 v45, v45, v93, s28
	v_bfe_u32 v93, v41, 16, 1
	v_add3_u32 v47, v47, v91, s28
	v_mov_b32_e32 v91, v92
	v_perm_b32 v237, v46, v45, s29
	v_bfe_u32 v46, v90, 16, 1
	v_add3_u32 v41, v41, v93, s28
	v_bfe_u32 v92, v91, 16, 1
	v_add3_u32 v90, v90, v46, s28
	v_perm_b32 v238, v41, v47, s29
	v_add3_u32 v41, v91, v92, s28
	v_perm_b32 v239, v41, v90, s29
	global_store_dwordx4 v[170:171], v[236:239], off
	v_pk_fma_f32 v[48:49], v[12:13], v[54:55], v[48:49]
	v_pk_fma_f32 v[64:65], v[14:15], v[72:73], v[64:65]
	v_pk_fma_f32 v[76:77], v[22:23], v[80:81], v[76:77]
	v_pk_fma_f32 v[50:51], v[8:9], v[54:55], v[50:51]
	v_pk_fma_f32 v[54:55], v[4:5], v[54:55], v[36:37]
	v_pk_fma_f32 v[74:75], v[10:11], v[72:73], v[74:75]
	v_pk_fma_f32 v[72:73], v[6:7], v[72:73], v[38:39]
	v_pk_fma_f32 v[78:79], v[18:19], v[80:81], v[78:79]
	v_pk_fma_f32 v[80:81], v[2:3], v[80:81], v[34:35]
	v_and_b32_e32 v71, 0xffff0000, v208
	v_lshlrev_b32_e32 v70, 16, v208
	v_and_b32_e32 v83, 0xffff0000, v209
	v_lshlrev_b32_e32 v82, 16, v209
	v_and_b32_e32 v45, 0xffff0000, v210
; DEVINL u16 f2bf(float f) { uint32_t u = __float_as_uint(f); u += 0x7FFFu + ((u >> 16) & 1u); return (u16)(u >> 16); }
; DEVINL float bfs2f(short h) { return __uint_as_float(((uint32_t)(u16)h) << 16); }
; DEVINL void phase_conv(const Params& p, int layer, int wv) {
;     ...
; #pragma unroll 8
;       for (int i = 0; i < 32; ++i) {
;         const bf16x8 r3 = *(const bf16x8*)(src + (size_t)i * HS);
;         bf16x8 o;
; #pragma unroll
;         for (int e = 0; e < 8; ++e) {
;           float v = bias[e] + w[0][e] * bfs2f(r0[e]) + w[1][e] * bfs2f(r1[e]) + w[2][e] * bfs2f(r2[e]) + w[3][e] * bfs2f(r3[e]);
;           v = v / (1.f + __expf(-v));
;           o[e] = (short)f2bf(v);
;         }
;         *(bf16x8*)(xc + (size_t)(tokA + i) * 1536 + ch0) = o;
;         r0 = r1; r1 = r2; r2 = r3;
;       }
	v_lshlrev_b32_e32 v44, 16, v210
	v_and_b32_e32 v91, 0xffff0000, v211
	v_lshlrev_b32_e32 v90, 16, v211
	v_pk_fma_f32 v[46:47], v[24:25], v[70:71], v[48:49]
	v_pk_fma_f32 v[48:49], v[26:27], v[82:83], v[64:65]
	v_pk_fma_f32 v[64:65], v[28:29], v[44:45], v[96:97]
	v_pk_fma_f32 v[92:93], v[20:21], v[44:45], v[98:99]
	v_pk_fma_f32 v[94:95], v[16:17], v[44:45], v[100:101]
	v_pk_fma_f32 v[96:97], v[0:1], v[44:45], v[32:33]
	v_mul_f32_e32 v41, 0xbfb8aa3b, v46
	v_mul_f32_e32 v45, 0xbfb8aa3b, v47
	v_exp_f32_e32 v44, v41
	v_exp_f32_e32 v45, v45
	v_mul_f32_e32 v98, 0xbfb8aa3b, v48
	v_mul_f32_e32 v99, 0xbfb8aa3b, v49
	v_exp_f32_e32 v98, v98
	v_exp_f32_e32 v99, v99
	v_mul_f32_e32 v100, 0xbfb8aa3b, v64
	v_mul_f32_e32 v101, 0xbfb8aa3b, v65
	v_pk_fma_f32 v[76:77], v[30:31], v[90:91], v[76:77]
	v_exp_f32_e32 v100, v100
	v_exp_f32_e32 v101, v101
	v_pk_add_f32 v[44:45], v[44:45], 1.0 op_sel_hi:[1,0]
	v_mul_f32_e32 v102, 0xbfb8aa3b, v76
	v_mul_f32_e32 v103, 0xbfb8aa3b, v77
	v_exp_f32_e32 v102, v102
	v_exp_f32_e32 v103, v103
	v_pk_add_f32 v[98:99], v[98:99], 1.0 op_sel_hi:[1,0]
	v_rcp_f32_e32 v119, v44
	v_rcp_f32_e32 v120, v45
	v_pk_add_f32 v[100:101], v[100:101], 1.0 op_sel_hi:[1,0]
	v_rcp_f32_e32 v121, v98
	v_rcp_f32_e32 v122, v99
	v_pk_add_f32 v[102:103], v[102:103], 1.0 op_sel_hi:[1,0]
	v_rcp_f32_e32 v123, v100
	v_rcp_f32_e32 v124, v101
	v_rcp_f32_e32 v125, v102
	v_rcp_f32_e32 v126, v103
	v_mul_f32_e32 v41, v46, v119
	s_mov_b64 vcc, s[0:1]
	v_mul_f32_e32 v44, v47, v120
	s_mov_b64 vcc, s[2:3]
	v_mul_f32_e32 v45, v48, v121
	s_mov_b64 vcc, s[4:5]
	v_bfe_u32 v46, v41, 16, 1
	v_mul_f32_e32 v47, v49, v122
	s_mov_b64 vcc, s[6:7]
	v_bfe_u32 v48, v44, 16, 1
	v_add3_u32 v41, v41, v46, s28
	v_mov_b32_e32 v46, v47
	v_mul_f32_e32 v47, v64, v123
	s_mov_b64 vcc, s[8:9]
	v_add3_u32 v44, v44, v48, s28
	v_mul_f32_e32 v48, v65, v124
	s_mov_b64 vcc, s[10:11]
	v_bfe_u32 v49, v45, 16, 1
	v_bfe_u32 v64, v46, 16, 1
	v_perm_b32 v240, v44, v41, s29
	v_mov_b32_e32 v41, v48
	v_mul_f32_e32 v48, v76, v125
	s_mov_b64 vcc, s[12:13]
	v_add3_u32 v45, v45, v49, s28
	v_bfe_u32 v49, v47, 16, 1
	v_add3_u32 v46, v46, v64, s28
	v_mul_f32_e32 v64, v77, v126
	v_bfe_u32 v65, v41, 16, 1
	v_add3_u32 v47, v47, v49, s28
	v_mov_b32_e32 v49, v64
	v_perm_b32 v241, v46, v45, s29
	v_bfe_u32 v46, v48, 16, 1
	v_add3_u32 v41, v41, v65, s28
	v_bfe_u32 v64, v49, 16, 1
	v_add3_u32 v48, v48, v46, s28
	v_perm_b32 v242, v41, v47, s29
	v_add3_u32 v41, v49, v64, s28
	v_perm_b32 v243, v41, v48, s29
	global_store_dwordx4 v[172:173], v[240:243], off
	v_pk_fma_f32 v[50:51], v[12:13], v[70:71], v[50:51]
	v_pk_fma_f32 v[54:55], v[8:9], v[70:71], v[54:55]
	v_pk_fma_f32 v[70:71], v[4:5], v[70:71], v[36:37]
	v_pk_fma_f32 v[74:75], v[14:15], v[82:83], v[74:75]
	v_pk_fma_f32 v[72:73], v[10:11], v[82:83], v[72:73]
	v_pk_fma_f32 v[82:83], v[6:7], v[82:83], v[38:39]
	v_pk_fma_f32 v[78:79], v[22:23], v[90:91], v[78:79]
	v_pk_fma_f32 v[80:81], v[18:19], v[90:91], v[80:81]
	v_pk_fma_f32 v[90:91], v[2:3], v[90:91], v[34:35]
	v_and_b32_e32 v49, 0xffff0000, v212
	v_lshlrev_b32_e32 v48, 16, v212
	v_pk_fma_f32 v[50:51], v[24:25], v[48:49], v[50:51]
	v_and_b32_e32 v65, 0xffff0000, v213
	v_lshlrev_b32_e32 v64, 16, v213
	v_pk_fma_f32 v[54:55], v[12:13], v[48:49], v[54:55]
	v_pk_fma_f32 v[70:71], v[8:9], v[48:49], v[70:71]
	v_mul_f32_e32 v41, 0xbfb8aa3b, v50
	v_mul_f32_e32 v49, 0xbfb8aa3b, v51
	v_pk_fma_f32 v[74:75], v[26:27], v[64:65], v[74:75]
	v_exp_f32_e32 v48, v41
	v_exp_f32_e32 v49, v49
	v_and_b32_e32 v69, 0xffff0000, v214
	v_lshlrev_b32_e32 v68, 16, v214
	v_pk_fma_f32 v[72:73], v[14:15], v[64:65], v[72:73]
	v_pk_fma_f32 v[64:65], v[10:11], v[64:65], v[82:83]
	v_mul_f32_e32 v82, 0xbfb8aa3b, v74
	v_mul_f32_e32 v83, 0xbfb8aa3b, v75
	v_and_b32_e32 v77, 0xffff0000, v215
	v_lshlrev_b32_e32 v76, 16, v215
	v_pk_fma_f32 v[84:85], v[28:29], v[68:69], v[92:93]
	v_exp_f32_e32 v82, v82
	v_exp_f32_e32 v83, v83
	v_pk_fma_f32 v[78:79], v[30:31], v[76:77], v[78:79]
	v_pk_fma_f32 v[80:81], v[22:23], v[76:77], v[80:81]
	v_pk_fma_f32 v[76:77], v[18:19], v[76:77], v[90:91]
	v_mul_f32_e32 v90, 0xbfb8aa3b, v84
	v_mul_f32_e32 v91, 0xbfb8aa3b, v85
	v_exp_f32_e32 v90, v90
	v_exp_f32_e32 v91, v91
	v_pk_add_f32 v[48:49], v[48:49], 1.0 op_sel_hi:[1,0]
	v_pk_fma_f32 v[92:93], v[20:21], v[68:69], v[94:95]
	v_mul_f32_e32 v94, 0xbfb8aa3b, v78
	v_mul_f32_e32 v95, 0xbfb8aa3b, v79
	v_pk_fma_f32 v[68:69], v[16:17], v[68:69], v[96:97]
	v_exp_f32_e32 v94, v94
	v_exp_f32_e32 v95, v95
	v_pk_add_f32 v[82:83], v[82:83], 1.0 op_sel_hi:[1,0]
	v_rcp_f32_e32 v111, v48
	v_rcp_f32_e32 v112, v49
	v_pk_add_f32 v[90:91], v[90:91], 1.0 op_sel_hi:[1,0]
	v_rcp_f32_e32 v113, v82
	v_rcp_f32_e32 v114, v83
	v_pk_add_f32 v[94:95], v[94:95], 1.0 op_sel_hi:[1,0]
	v_rcp_f32_e32 v115, v90
	v_rcp_f32_e32 v116, v91
	v_rcp_f32_e32 v117, v94
	v_rcp_f32_e32 v118, v95
	v_mul_f32_e32 v41, v50, v111
	s_mov_b64 vcc, s[0:1]
	v_mul_f32_e32 v48, v51, v112
	s_mov_b64 vcc, s[2:3]
	v_mul_f32_e32 v49, v74, v113
	s_mov_b64 vcc, s[4:5]
	v_bfe_u32 v50, v41, 16, 1
	v_mul_f32_e32 v51, v75, v114
	s_mov_b64 vcc, s[6:7]
	v_bfe_u32 v74, v48, 16, 1
	v_add3_u32 v41, v41, v50, s28
	v_mov_b32_e32 v50, v51
	v_mul_f32_e32 v51, v84, v115
	s_mov_b64 vcc, s[8:9]
	v_add3_u32 v48, v48, v74, s28
	v_mul_f32_e32 v74, v85, v116
	s_mov_b64 vcc, s[10:11]
	v_bfe_u32 v75, v49, 16, 1
	v_perm_b32 v244, v48, v41, s29
	v_mov_b32_e32 v41, v74
	v_mul_f32_e32 v74, v78, v117
	s_mov_b64 vcc, s[12:13]
	v_bfe_u32 v82, v50, 16, 1
	v_add3_u32 v49, v49, v75, s28
	v_bfe_u32 v75, v51, 16, 1
	v_mul_f32_e32 v78, v79, v118
	v_add3_u32 v50, v50, v82, s28
	v_bfe_u32 v82, v41, 16, 1
	v_add3_u32 v51, v51, v75, s28
	v_mov_b32_e32 v75, v78
	v_perm_b32 v245, v50, v49, s29
; DEVINL u16 f2bf(float f) { uint32_t u = __float_as_uint(f); u += 0x7FFFu + ((u >> 16) & 1u); return (u16)(u >> 16); }
; DEVINL float bfs2f(short h) { return __uint_as_float(((uint32_t)(u16)h) << 16); }
; DEVINL void phase_conv(const Params& p, int layer, int wv) {
;     ...
;     for (int run = blockIdx.x * 2 + half; run < T_TOK / 32; run += gridDim.x * 2) {
;       const int tokA = run * 32;
;       const int l0 = tokA & 4095;
;       const u16* src = hb + (size_t)tokA * HS + 1024 + ch0;
;       bf16x8 r0, r1, r2;
;       const bf16x8 zero8 = {0, 0, 0, 0, 0, 0, 0, 0};
;       r0 = (l0 >= 3) ? *(const bf16x8*)(src - 3 * (long)HS) : zero8;
;       r1 = (l0 >= 2) ? *(const bf16x8*)(src - 2 * (long)HS) : zero8;
;       r2 = (l0 >= 1) ? *(const bf16x8*)(src - 1 * (long)HS) : zero8;
; #pragma unroll 8
;       for (int i = 0; i < 32; ++i) {
;         const bf16x8 r3 = *(const bf16x8*)(src + (size_t)i * HS);
;         bf16x8 o;
; #pragma unroll
;         for (int e = 0; e < 8; ++e) {
;           float v = bias[e] + w[0][e] * bfs2f(r0[e]) + w[1][e] * bfs2f(r1[e]) + w[2][e] * bfs2f(r2[e]) + w[3][e] * bfs2f(r3[e]);
;           v = v / (1.f + __expf(-v));
;           o[e] = (short)f2bf(v);
;         }
;         *(bf16x8*)(xc + (size_t)(tokA + i) * 1536 + ch0) = o;
;         r0 = r1; r1 = r2; r2 = r3;
;       }
	v_bfe_u32 v50, v74, 16, 1
	v_add3_u32 v41, v41, v82, s28
	v_bfe_u32 v78, v75, 16, 1
	v_add3_u32 v74, v74, v50, s28
	v_perm_b32 v246, v41, v51, s29
	v_add3_u32 v41, v75, v78, s28
	v_perm_b32 v247, v41, v74, s29
	global_store_dwordx4 v[174:175], v[244:247], off
	v_and_b32_e32 v67, 0xffff0000, v216
	v_lshlrev_b32_e32 v66, 16, v216
	v_and_b32_e32 v75, 0xffff0000, v217
	v_lshlrev_b32_e32 v74, 16, v217
	v_pk_fma_f32 v[54:55], v[24:25], v[66:67], v[54:55]
	v_pk_fma_f32 v[72:73], v[26:27], v[74:75], v[72:73]
	v_pk_fma_f32 v[74:75], v[14:15], v[74:75], v[64:65]
	v_mul_f32_e32 v41, 0xbfb8aa3b, v54
	v_mul_f32_e32 v65, 0xbfb8aa3b, v55
	v_exp_f32_e32 v64, v41
	v_exp_f32_e32 v65, v65
	v_and_b32_e32 v79, 0xffff0000, v218
	v_lshlrev_b32_e32 v78, 16, v218
	v_pk_fma_f32 v[70:71], v[12:13], v[66:67], v[70:71]
	v_mul_f32_e32 v66, 0xbfb8aa3b, v72
	v_mul_f32_e32 v67, 0xbfb8aa3b, v73
	v_pk_fma_f32 v[84:85], v[28:29], v[78:79], v[92:93]
	v_exp_f32_e32 v66, v66
	v_exp_f32_e32 v67, v67
	v_and_b32_e32 v83, 0xffff0000, v219
	v_lshlrev_b32_e32 v82, 16, v219
	v_pk_fma_f32 v[68:69], v[20:21], v[78:79], v[68:69]
	v_mul_f32_e32 v78, 0xbfb8aa3b, v84
	v_mul_f32_e32 v79, 0xbfb8aa3b, v85
	v_pk_fma_f32 v[80:81], v[30:31], v[82:83], v[80:81]
	v_exp_f32_e32 v78, v78
	v_exp_f32_e32 v79, v79
	v_pk_add_f32 v[64:65], v[64:65], 1.0 op_sel_hi:[1,0]
	v_pk_fma_f32 v[76:77], v[22:23], v[82:83], v[76:77]
	v_mul_f32_e32 v82, 0xbfb8aa3b, v80
	v_mul_f32_e32 v83, 0xbfb8aa3b, v81
	v_exp_f32_e32 v82, v82
	v_exp_f32_e32 v83, v83
	v_pk_add_f32 v[66:67], v[66:67], 1.0 op_sel_hi:[1,0]
	v_rcp_f32_e32 v103, v64
	v_rcp_f32_e32 v104, v65
	v_pk_add_f32 v[78:79], v[78:79], 1.0 op_sel_hi:[1,0]
	v_rcp_f32_e32 v105, v66
	v_rcp_f32_e32 v106, v67
	v_pk_add_f32 v[82:83], v[82:83], 1.0 op_sel_hi:[1,0]
	v_rcp_f32_e32 v107, v78
	v_rcp_f32_e32 v108, v79
	v_rcp_f32_e32 v109, v82
	v_rcp_f32_e32 v110, v83
	v_mul_f32_e32 v41, v54, v103
	s_mov_b64 vcc, s[0:1]
	v_mul_f32_e32 v54, v55, v104
	s_mov_b64 vcc, s[2:3]
	v_mul_f32_e32 v55, v72, v105
	s_mov_b64 vcc, s[4:5]
	v_bfe_u32 v64, v41, 16, 1
	v_mul_f32_e32 v65, v73, v106
	s_mov_b64 vcc, s[6:7]
	v_bfe_u32 v66, v54, 16, 1
	v_add3_u32 v41, v41, v64, s28
	v_mul_f32_e32 v64, v84, v107
	s_mov_b64 vcc, s[8:9]
	v_add3_u32 v54, v54, v66, s28
	v_mul_f32_e32 v72, v85, v108
	s_mov_b64 vcc, s[10:11]
	v_bfe_u32 v67, v55, 16, 1
	v_mov_b32_e32 v66, v64
	v_bfe_u32 v73, v65, 16, 1
	v_perm_b32 v248, v54, v41, s29
	v_mul_f32_e32 v54, v80, v109
	s_mov_b64 vcc, s[12:13]
	v_add3_u32 v55, v55, v67, s28
	v_mov_b32_e32 v41, v72
	v_add3_u32 v65, v65, v73, s28
	v_mul_f32_e32 v72, v81, v110
	v_bfe_u32 v67, v66, 16, 1
	v_bfe_u32 v73, v41, 16, 1
	v_perm_b32 v249, v65, v55, s29
	v_mov_b32_e32 v55, v72
	v_add3_u32 v66, v66, v67, s28
	v_bfe_u32 v67, v54, 16, 1
	v_add3_u32 v41, v41, v73, s28
	v_bfe_u32 v72, v55, 16, 1
	v_add3_u32 v54, v54, v67, s28
	v_perm_b32 v250, v41, v66, s29
	v_add3_u32 v41, v55, v72, s28
	v_perm_b32 v251, v41, v54, s29
	global_store_dwordx4 v[178:179], v[248:251], off
	v_lshl_add_u64 v[42:43], v[42:43], 0, s[20:21]
	v_and_b32_e32 v65, 0xffff0000, v220
	v_lshlrev_b32_e32 v64, 16, v220
	v_and_b32_e32 v73, 0xffff0000, v222
	v_lshlrev_b32_e32 v72, 16, v222
	v_pk_fma_f32 v[64:65], v[24:25], v[64:65], v[70:71]
	v_and_b32_e32 v67, 0xffff0000, v221
	v_lshlrev_b32_e32 v66, 16, v221
	v_pk_fma_f32 v[68:69], v[28:29], v[72:73], v[68:69]
	v_mul_f32_e32 v41, 0xbfb8aa3b, v64
	v_mul_f32_e32 v73, 0xbfb8aa3b, v65
	v_pk_fma_f32 v[66:67], v[26:27], v[66:67], v[74:75]
	v_exp_f32_e32 v72, v41
	v_exp_f32_e32 v73, v73
	v_mul_f32_e32 v74, 0xbfb8aa3b, v66
	v_mul_f32_e32 v75, 0xbfb8aa3b, v67
	v_and_b32_e32 v79, 0xffff0000, v223
	v_lshlrev_b32_e32 v78, 16, v223
	v_exp_f32_e32 v74, v74
	v_exp_f32_e32 v75, v75
	v_pk_fma_f32 v[70:71], v[30:31], v[78:79], v[76:77]
	v_mul_f32_e32 v76, 0xbfb8aa3b, v68
	v_mul_f32_e32 v77, 0xbfb8aa3b, v69
	v_exp_f32_e32 v76, v76
	v_exp_f32_e32 v77, v77
	v_pk_add_f32 v[72:73], v[72:73], 1.0 op_sel_hi:[1,0]
	v_mul_f32_e32 v78, 0xbfb8aa3b, v70
	v_mul_f32_e32 v79, 0xbfb8aa3b, v71
	v_exp_f32_e32 v78, v78
	v_exp_f32_e32 v79, v79
	v_pk_add_f32 v[74:75], v[74:75], 1.0 op_sel_hi:[1,0]
	v_rcp_f32_e32 v97, v72
	v_rcp_f32_e32 v98, v73
	v_pk_add_f32 v[76:77], v[76:77], 1.0 op_sel_hi:[1,0]
	v_rcp_f32_e32 v99, v74
	v_rcp_f32_e32 v100, v75
	v_pk_add_f32 v[78:79], v[78:79], 1.0 op_sel_hi:[1,0]
	v_rcp_f32_e32 v101, v76
	v_rcp_f32_e32 v102, v77
	v_rcp_f32_e32 v103, v78
	v_rcp_f32_e32 v104, v79
	v_mul_f32_e32 v41, v64, v97
	s_mov_b64 vcc, s[0:1]
	v_mul_f32_e32 v64, v65, v98
	s_mov_b64 vcc, s[2:3]
	v_mul_f32_e32 v65, v66, v99
	s_mov_b64 vcc, s[4:5]
	v_mul_f32_e32 v66, v67, v100
	s_mov_b64 vcc, s[6:7]
	v_bfe_u32 v72, v41, 16, 1
	v_bfe_u32 v73, v64, 16, 1
	v_mul_f32_e32 v67, v68, v101
	s_mov_b64 vcc, s[8:9]
	v_add3_u32 v41, v41, v72, s28
	v_add3_u32 v64, v64, v73, s28
	v_mul_f32_e32 v68, v69, v102
	s_mov_b64 vcc, s[10:11]
	v_perm_b32 v160, v64, v41, s29
	v_mov_b32_e32 v41, v68
	v_mul_f32_e32 v68, v70, v103
	s_mov_b64 vcc, s[12:13]
	v_bfe_u32 v72, v65, 16, 1
	v_bfe_u32 v73, v66, 16, 1
	v_bfe_u32 v69, v67, 16, 1
	v_mul_f32_e32 v70, v71, v104
	v_add3_u32 v65, v65, v72, s28
	v_add3_u32 v66, v66, v73, s28
	v_bfe_u32 v72, v41, 16, 1
	v_add3_u32 v67, v67, v69, s28
	v_mov_b32_e32 v69, v70
	v_perm_b32 v161, v66, v65, s29
	v_bfe_u32 v66, v68, 16, 1
	v_add3_u32 v41, v41, v72, s28
	v_bfe_u32 v70, v69, 16, 1
	v_add3_u32 v68, v68, v66, s28
	v_perm_b32 v162, v41, v67, s29
	v_add3_u32 v41, v69, v70, s28
	v_perm_b32 v163, v41, v68, s29
	global_store_dwordx4 v[180:181], v[160:163], off
	s_cbranch_scc0 .LBB0_454
	v_add_u32_e32 v88, s22, v88
	v_cmp_lt_i32_e32 vcc, s35, v88
	s_or_b64 s[16:17], vcc, s[16:17]
	v_add_u32_e32 v89, s23, v89
	s_andn2_b64 exec, exec, s[16:17]
	s_cbranch_execnz .LBB0_447

; DEVINL u16 f2bf(float f) { uint32_t u = __float_as_uint(f); u += 0x7FFFu + ((u >> 16) & 1u); return (u16)(u >> 16); }
; DEVINL float bfs2f(short h) { return __uint_as_float(((uint32_t)(u16)h) << 16); }
; DEVINL void phase_conv(const Params& p, int layer, int wv) {
;     ...
;     for (int run = blockIdx.x * 2 + half; run < T_TOK / 32; run += gridDim.x * 2) {
;       const int tokA = run * 32;
;       const int l0 = tokA & 4095;
;       const u16* src = hb + (size_t)tokA * HS + 1024 + ch0;
;       bf16x8 r0, r1, r2;
;       const bf16x8 zero8 = {0, 0, 0, 0, 0, 0, 0, 0};
;       r0 = (l0 >= 3) ? *(const bf16x8*)(src - 3 * (long)HS) : zero8;
;       r1 = (l0 >= 2) ? *(const bf16x8*)(src - 2 * (long)HS) : zero8;
;       r2 = (l0 >= 1) ? *(const bf16x8*)(src - 1 * (long)HS) : zero8;
; #pragma unroll 8
;       for (int i = 0; i < 32; ++i) {
;         const bf16x8 r3 = *(const bf16x8*)(src + (size_t)i * HS);
;         bf16x8 o;
; #pragma unroll
;         for (int e = 0; e < 8; ++e) {
;           float v = bias[e] + w[0][e] * bfs2f(r0[e]) + w[1][e] * bfs2f(r1[e]) + w[2][e] * bfs2f(r2[e]) + w[3][e] * bfs2f(r3[e]);
;           v = v / (1.f + __expf(-v));
;           o[e] = (short)f2bf(v);
;         }
;         *(bf16x8*)(xc + (size_t)(tokA + i) * 1536 + ch0) = o;
;         r0 = r1; r1 = r2; r2 = r3;
;       }
.LBB0_1477:
	v_add_co_u32_e32 v62, vcc, 0xfffef000, v42
	s_waitcnt vmcnt(0)
	v_and_b32_e32 v69, 0xffff0000, v212
	v_addc_co_u32_e32 v63, vcc, -1, v43, vcc
	global_load_dwordx4 v[192:195], v[62:63], off offset:-2048
	v_lshlrev_b32_e32 v68, 16, v212
	v_and_b32_e32 v81, 0xffff0000, v215
	v_lshlrev_b32_e32 v80, 16, v215
	v_and_b32_e32 v67, 0xffff0000, v216
	v_lshlrev_b32_e32 v66, 16, v216
	v_and_b32_e32 v65, 0xffff0000, v220
	v_lshlrev_b32_e32 v64, 16, v220
	v_and_b32_e32 v73, 0xffff0000, v213
	v_lshlrev_b32_e32 v72, 16, v213
	v_and_b32_e32 v71, 0xffff0000, v217
	v_lshlrev_b32_e32 v70, 16, v217
	v_and_b32_e32 v45, 0xffff0000, v221
	v_lshlrev_b32_e32 v44, 16, v221
	v_and_b32_e32 v53, 0xffff0000, v218
	v_lshlrev_b32_e32 v52, 16, v218
	v_and_b32_e32 v79, 0xffff0000, v219
	v_lshlrev_b32_e32 v78, 16, v219
	v_pk_fma_f32 v[68:69], v[0:1], v[68:69], v[32:33]
	v_pk_fma_f32 v[80:81], v[10:11], v[80:81], v[38:39]
	v_and_b32_e32 v49, 0xffff0000, v222
	v_lshlrev_b32_e32 v48, 16, v222
	v_and_b32_e32 v77, 0xffff0000, v223
	v_lshlrev_b32_e32 v76, 16, v223
	v_pk_fma_f32 v[96:97], v[0:1], v[66:67], v[32:33]
	v_pk_fma_f32 v[98:99], v[2:3], v[70:71], v[34:35]
	v_pk_fma_f32 v[100:101], v[8:9], v[52:53], v[36:37]
	v_pk_fma_f32 v[102:103], v[10:11], v[78:79], v[38:39]
	v_pk_fma_f32 v[112:113], v[4:5], v[66:67], v[68:69]
	v_pk_fma_f32 v[78:79], v[14:15], v[78:79], v[80:81]
	v_add_u32_e32 v41, s38, v89
	v_pk_fma_f32 v[72:73], v[2:3], v[72:73], v[34:35]
	v_pk_fma_f32 v[104:105], v[0:1], v[64:65], v[32:33]
	v_pk_fma_f32 v[110:111], v[10:11], v[76:77], v[38:39]
	v_pk_fma_f32 v[80:81], v[4:5], v[64:65], v[96:97]
	v_pk_fma_f32 v[96:97], v[6:7], v[44:45], v[98:99]
	v_pk_fma_f32 v[98:99], v[12:13], v[48:49], v[100:101]
	v_pk_fma_f32 v[100:101], v[14:15], v[76:77], v[102:103]
	v_pk_fma_f32 v[64:65], v[16:17], v[64:65], v[112:113]
	v_pk_fma_f32 v[76:77], v[26:27], v[76:77], v[78:79]
	v_and_b32_e32 v75, 0xffff0000, v214
	v_lshlrev_b32_e32 v74, 16, v214
	v_mad_i64_i32 v[164:165], s[0:1], v41, s33, v[58:59]
	v_add_u32_e32 v118, 1, v41
	v_add_u32_e32 v119, 2, v41
	v_add_u32_e32 v120, 3, v41
	v_add_u32_e32 v121, 4, v41
	v_add_u32_e32 v122, 5, v41
	v_add_u32_e32 v123, 6, v41
	v_add_u32_e32 v41, 7, v41
	v_pk_fma_f32 v[114:115], v[6:7], v[70:71], v[72:73]
	v_pk_fma_f32 v[74:75], v[8:9], v[74:75], v[36:37]
	v_pk_fma_f32 v[106:107], v[2:3], v[44:45], v[34:35]
	v_mad_i64_i32 v[180:181], s[0:1], v41, s33, v[58:59]
	v_pk_fma_f32 v[44:45], v[18:19], v[44:45], v[114:115]
	v_add_co_u32_e64 v46, s[2:3], s34, v42
	v_pk_fma_f32 v[116:117], v[12:13], v[52:53], v[74:75]
	s_nop 0
	v_addc_co_u32_e64 v47, s[2:3], -1, v43, s[2:3]
	v_pk_fma_f32 v[108:109], v[8:9], v[48:49], v[36:37]
	v_pk_fma_f32 v[48:49], v[24:25], v[48:49], v[116:117]
	v_add_co_u32_e64 v50, s[2:3], s35, v42
	v_mad_i64_i32 v[166:167], s[0:1], v118, s33, v[58:59]
	s_nop 0
	v_addc_co_u32_e64 v51, s[2:3], -1, v43, s[2:3]
	v_add_co_u32_e64 v54, s[2:3], s36, v42
	v_mad_i64_i32 v[168:169], s[0:1], v119, s33, v[58:59]
	s_nop 0
	v_addc_co_u32_e64 v55, s[2:3], -1, v43, s[2:3]
	v_add_co_u32_e64 v82, s[2:3], s27, v42
	v_mad_i64_i32 v[172:173], s[0:1], v121, s33, v[58:59]
	s_waitcnt vmcnt(0)
	v_and_b32_e32 v79, 0xffff0000, v192
	v_lshlrev_b32_e32 v78, 16, v192
	v_and_b32_e32 v113, 0xffff0000, v195
	v_lshlrev_b32_e32 v112, 16, v195
	v_pk_fma_f32 v[64:65], v[20:21], v[78:79], v[64:65]
	v_and_b32_e32 v103, 0xffff0000, v193
	v_lshlrev_b32_e32 v102, 16, v193
	v_and_b32_e32 v91, 0xffff0000, v194
	v_lshlrev_b32_e32 v90, 16, v194
	v_pk_fma_f32 v[92:93], v[30:31], v[112:113], v[76:77]
	v_mul_f32_e32 v41, 0xbfb8aa3b, v64
	v_mul_f32_e32 v77, 0xbfb8aa3b, v65
	v_pk_fma_f32 v[44:45], v[22:23], v[102:103], v[44:45]
	v_exp_f32_e32 v76, v41
	v_exp_f32_e32 v77, v77
	v_pk_fma_f32 v[80:81], v[16:17], v[78:79], v[80:81]
	v_pk_fma_f32 v[104:105], v[4:5], v[78:79], v[104:105]
	v_pk_fma_f32 v[114:115], v[0:1], v[78:79], v[32:33]
	v_mul_f32_e32 v78, 0xbfb8aa3b, v44
	v_mul_f32_e32 v79, 0xbfb8aa3b, v45
	v_pk_fma_f32 v[48:49], v[28:29], v[90:91], v[48:49]
	v_exp_f32_e32 v78, v78
	v_exp_f32_e32 v79, v79
	v_mul_f32_e32 v116, 0xbfb8aa3b, v48
	v_mul_f32_e32 v117, 0xbfb8aa3b, v49
	v_exp_f32_e32 v116, v116
	v_exp_f32_e32 v117, v117
	v_pk_add_f32 v[76:77], v[76:77], 1.0 op_sel_hi:[1,0]
	v_mul_f32_e32 v118, 0xbfb8aa3b, v92
	v_mul_f32_e32 v119, 0xbfb8aa3b, v93
	v_exp_f32_e32 v118, v118
	v_exp_f32_e32 v119, v119
	v_pk_add_f32 v[78:79], v[78:79], 1.0 op_sel_hi:[1,0]
	v_rcp_f32_e32 v135, v76
	v_addc_co_u32_e64 v83, s[2:3], -1, v43, s[2:3]
	v_mad_i64_i32 v[178:179], s[0:1], v123, s33, v[58:59]
	v_rcp_f32_e32 v136, v77
	v_add_co_u32_e64 v84, s[2:3], s28, v42
	v_pk_add_f32 v[116:117], v[116:117], 1.0 op_sel_hi:[1,0]
	v_rcp_f32_e32 v137, v78
	v_addc_co_u32_e64 v85, s[2:3], -1, v43, s[2:3]
	v_rcp_f32_e32 v138, v79
	v_add_co_u32_e64 v86, s[2:3], s29, v42
	v_pk_add_f32 v[118:119], v[118:119], 1.0 op_sel_hi:[1,0]
	v_rcp_f32_e32 v139, v116
	v_addc_co_u32_e64 v87, s[2:3], -1, v43, s[2:3]
	global_load_dwordx4 v[196:199], v[46:47], off
	global_load_dwordx4 v[200:203], v[50:51], off offset:-2048
	global_load_dwordx4 v[204:207], v[54:55], off
	global_load_dwordx4 v[208:211], v[82:83], off offset:-2048
	global_load_dwordx4 v[212:215], v[84:85], off
	global_load_dwordx4 v[216:219], v[86:87], off offset:-2048
	global_load_dwordx4 v[220:223], v[42:43], off
	v_mad_i64_i32 v[170:171], s[0:1], v120, s33, v[58:59]
	v_rcp_f32_e32 v140, v117
	v_mad_i64_i32 v[174:175], s[0:1], v122, s33, v[58:59]
	v_rcp_f32_e32 v141, v118
	v_rcp_f32_e32 v142, v119
	v_mul_f32_e32 v41, v64, v135
	s_mov_b64 vcc, s[2:3]
	v_mul_f32_e32 v64, v65, v136
	s_mov_b64 vcc, s[4:5]
	v_mul_f32_e32 v65, v44, v137
	s_mov_b64 vcc, s[6:7]
; DEVINL u16 f2bf(float f) { uint32_t u = __float_as_uint(f); u += 0x7FFFu + ((u >> 16) & 1u); return (u16)(u >> 16); }
; DEVINL float bfs2f(short h) { return __uint_as_float(((uint32_t)(u16)h) << 16); }
; DEVINL void phase_conv(const Params& p, int layer, int wv) {
;     ...
; #pragma unroll 8
;       for (int i = 0; i < 32; ++i) {
;         const bf16x8 r3 = *(const bf16x8*)(src + (size_t)i * HS);
;         bf16x8 o;
; #pragma unroll
;         for (int e = 0; e < 8; ++e) {
;           float v = bias[e] + w[0][e] * bfs2f(r0[e]) + w[1][e] * bfs2f(r1[e]) + w[2][e] * bfs2f(r2[e]) + w[3][e] * bfs2f(r3[e]);
;           v = v / (1.f + __expf(-v));
;           o[e] = (short)f2bf(v);
;         }
;         *(bf16x8*)(xc + (size_t)(tokA + i) * 1536 + ch0) = o;
;         r0 = r1; r1 = r2; r2 = r3;
;       }
	v_mov_b32_e32 v44, v65
	v_mul_f32_e32 v65, v45, v138
	s_mov_b64 vcc, s[8:9]
	v_bfe_u32 v76, v41, 16, 1
	v_bfe_u32 v77, v64, 16, 1
	v_mov_b32_e32 v45, v65
	v_mul_f32_e32 v65, v48, v139
	s_mov_b64 vcc, s[10:11]
	v_add3_u32 v41, v41, v76, s30
	v_bfe_u32 v76, v44, 16, 1
	v_add3_u32 v64, v64, v77, s30
	v_mov_b32_e32 v48, v65
	v_mul_f32_e32 v65, v49, v140
	s_mov_b64 vcc, s[12:13]
	v_bfe_u32 v77, v45, 16, 1
	v_add3_u32 v44, v44, v76, s30
	v_perm_b32 v224, v64, v41, s31
	v_mov_b32_e32 v41, v65
	v_mul_f32_e32 v49, v92, v141
	s_mov_b64 vcc, s[14:15]
	v_add3_u32 v45, v45, v77, s30
	v_mul_f32_e32 v65, v93, v142
	v_bfe_u32 v64, v48, 16, 1
	v_bfe_u32 v78, v41, 16, 1
	v_perm_b32 v225, v45, v44, s31
	v_mov_b32_e32 v44, v65
	v_add3_u32 v48, v48, v64, s30
	v_bfe_u32 v45, v49, 16, 1
	v_add3_u32 v41, v41, v78, s30
	v_bfe_u32 v64, v44, 16, 1
	v_add3_u32 v45, v49, v45, s30
	v_perm_b32 v226, v41, v48, s31
	v_add3_u32 v41, v44, v64, s30
	v_perm_b32 v227, v41, v45, s31
	global_store_dwordx4 v[164:165], v[224:227], off
	v_pk_fma_f32 v[98:99], v[24:25], v[90:91], v[98:99]
	v_pk_fma_f32 v[108:109], v[12:13], v[90:91], v[108:109]
	v_pk_fma_f32 v[90:91], v[8:9], v[90:91], v[36:37]
	v_pk_fma_f32 v[96:97], v[18:19], v[102:103], v[96:97]
	v_pk_fma_f32 v[100:101], v[26:27], v[112:113], v[100:101]
	v_pk_fma_f32 v[110:111], v[14:15], v[112:113], v[110:111]
	v_pk_fma_f32 v[106:107], v[6:7], v[102:103], v[106:107]
	v_pk_fma_f32 v[112:113], v[10:11], v[112:113], v[38:39]
	v_pk_fma_f32 v[102:103], v[2:3], v[102:103], v[34:35]
	s_add_i32 s38, s38, 8
	s_cmp_eq_u32 s38, 32
	s_waitcnt vmcnt(0)
	v_and_b32_e32 v49, 0xffff0000, v196
	v_lshlrev_b32_e32 v48, 16, v196
	v_and_b32_e32 v65, 0xffff0000, v197
	v_lshlrev_b32_e32 v64, 16, v197
	v_and_b32_e32 v45, 0xffff0000, v198
	v_lshlrev_b32_e32 v44, 16, v198
	v_and_b32_e32 v77, 0xffff0000, v199
	v_lshlrev_b32_e32 v76, 16, v199
	v_pk_fma_f32 v[46:47], v[20:21], v[48:49], v[80:81]
	v_pk_fma_f32 v[80:81], v[28:29], v[44:45], v[98:99]
	v_pk_fma_f32 v[98:99], v[24:25], v[44:45], v[108:109]
	v_pk_fma_f32 v[90:91], v[12:13], v[44:45], v[90:91]
	v_pk_fma_f32 v[108:109], v[8:9], v[44:45], v[36:37]
	v_mul_f32_e32 v41, 0xbfb8aa3b, v46
	v_mul_f32_e32 v45, 0xbfb8aa3b, v47
	v_pk_fma_f32 v[78:79], v[22:23], v[64:65], v[96:97]
	v_exp_f32_e32 v44, v41
	v_exp_f32_e32 v45, v45
	v_pk_fma_f32 v[92:93], v[30:31], v[76:77], v[100:101]
	v_pk_fma_f32 v[100:101], v[26:27], v[76:77], v[110:111]
	v_mul_f32_e32 v110, 0xbfb8aa3b, v78
	v_mul_f32_e32 v111, 0xbfb8aa3b, v79
	v_exp_f32_e32 v110, v110
	v_exp_f32_e32 v111, v111
	v_pk_fma_f32 v[96:97], v[18:19], v[64:65], v[106:107]
	v_pk_fma_f32 v[106:107], v[14:15], v[76:77], v[112:113]
	v_mul_f32_e32 v112, 0xbfb8aa3b, v80
	v_mul_f32_e32 v113, 0xbfb8aa3b, v81
	v_exp_f32_e32 v112, v112
	v_exp_f32_e32 v113, v113
	v_pk_add_f32 v[44:45], v[44:45], 1.0 op_sel_hi:[1,0]
	v_pk_fma_f32 v[94:95], v[16:17], v[48:49], v[104:105]
	v_pk_fma_f32 v[104:105], v[4:5], v[48:49], v[114:115]
	v_mul_f32_e32 v114, 0xbfb8aa3b, v92
	v_mul_f32_e32 v115, 0xbfb8aa3b, v93
	v_exp_f32_e32 v114, v114
	v_exp_f32_e32 v115, v115
	v_pk_add_f32 v[110:111], v[110:111], 1.0 op_sel_hi:[1,0]
	v_rcp_f32_e32 v131, v44
	v_rcp_f32_e32 v132, v45
	v_pk_add_f32 v[112:113], v[112:113], 1.0 op_sel_hi:[1,0]
	v_rcp_f32_e32 v133, v110
	v_rcp_f32_e32 v134, v111
	v_pk_add_f32 v[114:115], v[114:115], 1.0 op_sel_hi:[1,0]
	v_rcp_f32_e32 v135, v112
	v_rcp_f32_e32 v136, v113
	v_rcp_f32_e32 v137, v114
	v_rcp_f32_e32 v138, v115
	v_mul_f32_e32 v41, v46, v131
	s_mov_b64 vcc, s[2:3]
	v_mul_f32_e32 v44, v47, v132
	s_mov_b64 vcc, s[4:5]
	v_mul_f32_e32 v45, v78, v133
	s_mov_b64 vcc, s[6:7]
	v_bfe_u32 v46, v41, 16, 1
	v_mul_f32_e32 v47, v79, v134
	s_mov_b64 vcc, s[8:9]
	v_bfe_u32 v78, v44, 16, 1
	v_add3_u32 v41, v41, v46, s30
	v_mov_b32_e32 v46, v47
	v_mul_f32_e32 v47, v80, v135
	s_mov_b64 vcc, s[10:11]
	v_add3_u32 v44, v44, v78, s30
	v_mul_f32_e32 v78, v81, v136
	s_mov_b64 vcc, s[12:13]
	v_bfe_u32 v79, v45, 16, 1
	v_bfe_u32 v80, v46, 16, 1
	v_perm_b32 v228, v44, v41, s31
	v_mov_b32_e32 v41, v78
	v_mul_f32_e32 v78, v92, v137
	s_mov_b64 vcc, s[14:15]
	v_add3_u32 v45, v45, v79, s30
	v_bfe_u32 v79, v47, 16, 1
	v_add3_u32 v46, v46, v80, s30
	v_mul_f32_e32 v80, v93, v138
	v_bfe_u32 v81, v41, 16, 1
	v_add3_u32 v47, v47, v79, s30
	v_mov_b32_e32 v79, v80
	v_perm_b32 v229, v46, v45, s31
	v_bfe_u32 v46, v78, 16, 1
	v_add3_u32 v41, v41, v81, s30
	v_bfe_u32 v80, v79, 16, 1
	v_add3_u32 v78, v78, v46, s30
	v_perm_b32 v230, v41, v47, s31
	v_add3_u32 v41, v79, v80, s30
	v_perm_b32 v231, v41, v78, s31
	global_store_dwordx4 v[166:167], v[228:231], off
	v_pk_fma_f32 v[102:103], v[6:7], v[64:65], v[102:103]
	v_pk_fma_f32 v[48:49], v[0:1], v[48:49], v[32:33]
	v_pk_fma_f32 v[64:65], v[2:3], v[64:65], v[34:35]
	v_pk_fma_f32 v[76:77], v[10:11], v[76:77], v[38:39]
	v_and_b32_e32 v51, 0xffff0000, v200
	v_lshlrev_b32_e32 v50, 16, v200
	v_and_b32_e32 v75, 0xffff0000, v201
	v_lshlrev_b32_e32 v74, 16, v201
	v_and_b32_e32 v45, 0xffff0000, v202
	v_lshlrev_b32_e32 v44, 16, v202
	v_and_b32_e32 v79, 0xffff0000, v203
	v_lshlrev_b32_e32 v78, 16, v203
	v_pk_fma_f32 v[46:47], v[20:21], v[50:51], v[94:95]
	v_pk_fma_f32 v[80:81], v[22:23], v[74:75], v[96:97]
	v_pk_fma_f32 v[92:93], v[28:29], v[44:45], v[98:99]
	v_pk_fma_f32 v[96:97], v[16:17], v[50:51], v[104:105]
	v_pk_fma_f32 v[98:99], v[18:19], v[74:75], v[102:103]
	v_pk_fma_f32 v[90:91], v[24:25], v[44:45], v[90:91]
	v_pk_fma_f32 v[102:103], v[12:13], v[44:45], v[108:109]
	v_pk_fma_f32 v[104:105], v[8:9], v[44:45], v[36:37]
	v_mul_f32_e32 v41, 0xbfb8aa3b, v46
	v_mul_f32_e32 v45, 0xbfb8aa3b, v47
	v_exp_f32_e32 v44, v41
	v_exp_f32_e32 v45, v45
	v_pk_fma_f32 v[94:95], v[30:31], v[78:79], v[100:101]
; DEVINL u16 f2bf(float f) { uint32_t u = __float_as_uint(f); u += 0x7FFFu + ((u >> 16) & 1u); return (u16)(u >> 16); }
; DEVINL float bfs2f(short h) { return __uint_as_float(((uint32_t)(u16)h) << 16); }
; DEVINL void phase_conv(const Params& p, int layer, int wv) {
;     ...
; #pragma unroll 8
;       for (int i = 0; i < 32; ++i) {
;         const bf16x8 r3 = *(const bf16x8*)(src + (size_t)i * HS);
;         bf16x8 o;
; #pragma unroll
;         for (int e = 0; e < 8; ++e) {
;           float v = bias[e] + w[0][e] * bfs2f(r0[e]) + w[1][e] * bfs2f(r1[e]) + w[2][e] * bfs2f(r2[e]) + w[3][e] * bfs2f(r3[e]);
;           v = v / (1.f + __expf(-v));
;           o[e] = (short)f2bf(v);
;         }
;         *(bf16x8*)(xc + (size_t)(tokA + i) * 1536 + ch0) = o;
;         r0 = r1; r1 = r2; r2 = r3;
;       }
	v_pk_fma_f32 v[100:101], v[26:27], v[78:79], v[106:107]
	v_mul_f32_e32 v106, 0xbfb8aa3b, v80
	v_mul_f32_e32 v107, 0xbfb8aa3b, v81
	v_exp_f32_e32 v106, v106
	v_exp_f32_e32 v107, v107
	v_mul_f32_e32 v108, 0xbfb8aa3b, v92
	v_mul_f32_e32 v109, 0xbfb8aa3b, v93
	v_exp_f32_e32 v108, v108
	v_exp_f32_e32 v109, v109
	v_pk_add_f32 v[44:45], v[44:45], 1.0 op_sel_hi:[1,0]
	v_mul_f32_e32 v110, 0xbfb8aa3b, v94
	v_mul_f32_e32 v111, 0xbfb8aa3b, v95
	v_exp_f32_e32 v110, v110
	v_exp_f32_e32 v111, v111
	v_pk_add_f32 v[106:107], v[106:107], 1.0 op_sel_hi:[1,0]
	v_rcp_f32_e32 v127, v44
	v_rcp_f32_e32 v128, v45
	v_pk_add_f32 v[108:109], v[108:109], 1.0 op_sel_hi:[1,0]
	v_rcp_f32_e32 v129, v106
	v_rcp_f32_e32 v130, v107
	v_pk_add_f32 v[110:111], v[110:111], 1.0 op_sel_hi:[1,0]
	v_rcp_f32_e32 v131, v108
	v_rcp_f32_e32 v132, v109
	v_rcp_f32_e32 v133, v110
	v_rcp_f32_e32 v134, v111
	v_mul_f32_e32 v41, v46, v127
	s_mov_b64 vcc, s[2:3]
	v_mul_f32_e32 v44, v47, v128
	s_mov_b64 vcc, s[4:5]
	v_mul_f32_e32 v45, v80, v129
	s_mov_b64 vcc, s[6:7]
	v_bfe_u32 v46, v41, 16, 1
	v_mul_f32_e32 v47, v81, v130
	s_mov_b64 vcc, s[8:9]
	v_bfe_u32 v80, v44, 16, 1
	v_add3_u32 v41, v41, v46, s30
	v_mov_b32_e32 v46, v47
	v_mul_f32_e32 v47, v92, v131
	s_mov_b64 vcc, s[10:11]
	v_add3_u32 v44, v44, v80, s30
	v_mul_f32_e32 v80, v93, v132
	s_mov_b64 vcc, s[12:13]
	v_bfe_u32 v81, v45, 16, 1
	v_bfe_u32 v92, v46, 16, 1
	v_perm_b32 v232, v44, v41, s31
	v_mov_b32_e32 v41, v80
	v_mul_f32_e32 v80, v94, v133
	s_mov_b64 vcc, s[14:15]
	v_add3_u32 v45, v45, v81, s30
	v_bfe_u32 v81, v47, 16, 1
	v_add3_u32 v46, v46, v92, s30
	v_mul_f32_e32 v92, v95, v134
	v_bfe_u32 v93, v41, 16, 1
	v_add3_u32 v47, v47, v81, s30
	v_mov_b32_e32 v81, v92
	v_perm_b32 v233, v46, v45, s31
	v_bfe_u32 v46, v80, 16, 1
	v_add3_u32 v41, v41, v93, s30
	v_bfe_u32 v92, v81, 16, 1
	v_add3_u32 v80, v80, v46, s30
	v_perm_b32 v234, v41, v47, s31
	v_add3_u32 v41, v81, v92, s30
	v_perm_b32 v235, v41, v80, s31
	global_store_dwordx4 v[168:169], v[232:235], off
	v_pk_fma_f32 v[48:49], v[4:5], v[50:51], v[48:49]
	v_pk_fma_f32 v[64:65], v[6:7], v[74:75], v[64:65]
	v_pk_fma_f32 v[76:77], v[14:15], v[78:79], v[76:77]
	v_pk_fma_f32 v[50:51], v[0:1], v[50:51], v[32:33]
	v_pk_fma_f32 v[74:75], v[2:3], v[74:75], v[34:35]
	v_pk_fma_f32 v[78:79], v[10:11], v[78:79], v[38:39]
	v_and_b32_e32 v55, 0xffff0000, v204
	v_lshlrev_b32_e32 v54, 16, v204
	v_and_b32_e32 v73, 0xffff0000, v205
	v_lshlrev_b32_e32 v72, 16, v205
	v_and_b32_e32 v45, 0xffff0000, v206
	v_lshlrev_b32_e32 v44, 16, v206
	v_and_b32_e32 v81, 0xffff0000, v207
	v_lshlrev_b32_e32 v80, 16, v207
	v_pk_fma_f32 v[46:47], v[20:21], v[54:55], v[96:97]
	v_pk_fma_f32 v[92:93], v[22:23], v[72:73], v[98:99]
	v_pk_fma_f32 v[90:91], v[28:29], v[44:45], v[90:91]
	v_pk_fma_f32 v[94:95], v[30:31], v[80:81], v[100:101]
	v_pk_fma_f32 v[96:97], v[24:25], v[44:45], v[102:103]
	v_pk_fma_f32 v[98:99], v[12:13], v[44:45], v[104:105]
	v_pk_fma_f32 v[100:101], v[8:9], v[44:45], v[36:37]
	v_mul_f32_e32 v41, 0xbfb8aa3b, v46
	v_mul_f32_e32 v45, 0xbfb8aa3b, v47
	v_exp_f32_e32 v44, v41
	v_exp_f32_e32 v45, v45
	v_mul_f32_e32 v102, 0xbfb8aa3b, v92
	v_mul_f32_e32 v103, 0xbfb8aa3b, v93
	v_exp_f32_e32 v102, v102
	v_exp_f32_e32 v103, v103
	v_mul_f32_e32 v104, 0xbfb8aa3b, v90
	v_mul_f32_e32 v105, 0xbfb8aa3b, v91
	v_exp_f32_e32 v104, v104
	v_exp_f32_e32 v105, v105
	v_pk_add_f32 v[44:45], v[44:45], 1.0 op_sel_hi:[1,0]
	v_mul_f32_e32 v106, 0xbfb8aa3b, v94
	v_mul_f32_e32 v107, 0xbfb8aa3b, v95
	v_exp_f32_e32 v106, v106
	v_exp_f32_e32 v107, v107
	v_pk_add_f32 v[102:103], v[102:103], 1.0 op_sel_hi:[1,0]
	v_rcp_f32_e32 v123, v44
	v_rcp_f32_e32 v124, v45
	v_pk_add_f32 v[104:105], v[104:105], 1.0 op_sel_hi:[1,0]
	v_rcp_f32_e32 v125, v102
	v_rcp_f32_e32 v126, v103
	v_pk_add_f32 v[106:107], v[106:107], 1.0 op_sel_hi:[1,0]
	v_rcp_f32_e32 v127, v104
	v_rcp_f32_e32 v128, v105
	v_rcp_f32_e32 v129, v106
	v_rcp_f32_e32 v130, v107
	v_mul_f32_e32 v41, v46, v123
	s_mov_b64 vcc, s[2:3]
	v_mul_f32_e32 v44, v47, v124
	s_mov_b64 vcc, s[4:5]
	v_mul_f32_e32 v45, v92, v125
	s_mov_b64 vcc, s[6:7]
	v_bfe_u32 v46, v41, 16, 1
	v_mul_f32_e32 v47, v93, v126
	s_mov_b64 vcc, s[8:9]
	v_bfe_u32 v92, v44, 16, 1
	v_add3_u32 v41, v41, v46, s30
	v_mov_b32_e32 v46, v47
	v_mul_f32_e32 v47, v90, v127
	s_mov_b64 vcc, s[10:11]
	v_add3_u32 v44, v44, v92, s30
	v_mul_f32_e32 v90, v91, v128
	s_mov_b64 vcc, s[12:13]
	v_bfe_u32 v92, v46, 16, 1
	v_perm_b32 v236, v44, v41, s31
	v_mov_b32_e32 v41, v90
	v_mul_f32_e32 v90, v94, v129
	s_mov_b64 vcc, s[14:15]
	v_bfe_u32 v93, v45, 16, 1
	v_bfe_u32 v91, v47, 16, 1
	v_add3_u32 v46, v46, v92, s30
	v_mul_f32_e32 v92, v95, v130
	v_add3_u32 v45, v45, v93, s30
	v_bfe_u32 v93, v41, 16, 1
	v_add3_u32 v47, v47, v91, s30
	v_mov_b32_e32 v91, v92
	v_perm_b32 v237, v46, v45, s31
	v_bfe_u32 v46, v90, 16, 1
	v_add3_u32 v41, v41, v93, s30
	v_bfe_u32 v92, v91, 16, 1
	v_add3_u32 v90, v90, v46, s30
	v_perm_b32 v238, v41, v47, s31
	v_add3_u32 v41, v91, v92, s30
	v_perm_b32 v239, v41, v90, s31
	global_store_dwordx4 v[170:171], v[236:239], off
	v_pk_fma_f32 v[48:49], v[16:17], v[54:55], v[48:49]
	v_pk_fma_f32 v[64:65], v[18:19], v[72:73], v[64:65]
	v_pk_fma_f32 v[76:77], v[26:27], v[80:81], v[76:77]
	v_pk_fma_f32 v[50:51], v[4:5], v[54:55], v[50:51]
	v_pk_fma_f32 v[54:55], v[0:1], v[54:55], v[32:33]
	v_pk_fma_f32 v[74:75], v[6:7], v[72:73], v[74:75]
	v_pk_fma_f32 v[72:73], v[2:3], v[72:73], v[34:35]
	v_pk_fma_f32 v[78:79], v[14:15], v[80:81], v[78:79]
	v_pk_fma_f32 v[80:81], v[10:11], v[80:81], v[38:39]
	v_and_b32_e32 v71, 0xffff0000, v208
	v_lshlrev_b32_e32 v70, 16, v208
	v_and_b32_e32 v83, 0xffff0000, v209
	v_lshlrev_b32_e32 v82, 16, v209
	v_and_b32_e32 v45, 0xffff0000, v210
; DEVINL u16 f2bf(float f) { uint32_t u = __float_as_uint(f); u += 0x7FFFu + ((u >> 16) & 1u); return (u16)(u >> 16); }
; DEVINL float bfs2f(short h) { return __uint_as_float(((uint32_t)(u16)h) << 16); }
; DEVINL void phase_conv(const Params& p, int layer, int wv) {
;     ...
; #pragma unroll 8
;       for (int i = 0; i < 32; ++i) {
;         const bf16x8 r3 = *(const bf16x8*)(src + (size_t)i * HS);
;         bf16x8 o;
; #pragma unroll
;         for (int e = 0; e < 8; ++e) {
;           float v = bias[e] + w[0][e] * bfs2f(r0[e]) + w[1][e] * bfs2f(r1[e]) + w[2][e] * bfs2f(r2[e]) + w[3][e] * bfs2f(r3[e]);
;           v = v / (1.f + __expf(-v));
;           o[e] = (short)f2bf(v);
;         }
;         *(bf16x8*)(xc + (size_t)(tokA + i) * 1536 + ch0) = o;
;         r0 = r1; r1 = r2; r2 = r3;
;       }
	v_lshlrev_b32_e32 v44, 16, v210
	v_and_b32_e32 v91, 0xffff0000, v211
	v_lshlrev_b32_e32 v90, 16, v211
	v_pk_fma_f32 v[46:47], v[20:21], v[70:71], v[48:49]
	v_pk_fma_f32 v[48:49], v[22:23], v[82:83], v[64:65]
	v_pk_fma_f32 v[64:65], v[28:29], v[44:45], v[96:97]
	v_pk_fma_f32 v[92:93], v[24:25], v[44:45], v[98:99]
	v_pk_fma_f32 v[94:95], v[12:13], v[44:45], v[100:101]
	v_pk_fma_f32 v[96:97], v[8:9], v[44:45], v[36:37]
	v_mul_f32_e32 v41, 0xbfb8aa3b, v46
	v_mul_f32_e32 v45, 0xbfb8aa3b, v47
	v_exp_f32_e32 v44, v41
	v_exp_f32_e32 v45, v45
	v_mul_f32_e32 v98, 0xbfb8aa3b, v48
	v_mul_f32_e32 v99, 0xbfb8aa3b, v49
	v_exp_f32_e32 v98, v98
	v_exp_f32_e32 v99, v99
	v_mul_f32_e32 v100, 0xbfb8aa3b, v64
	v_mul_f32_e32 v101, 0xbfb8aa3b, v65
	v_pk_fma_f32 v[76:77], v[30:31], v[90:91], v[76:77]
	v_exp_f32_e32 v100, v100
	v_exp_f32_e32 v101, v101
	v_pk_add_f32 v[44:45], v[44:45], 1.0 op_sel_hi:[1,0]
	v_mul_f32_e32 v102, 0xbfb8aa3b, v76
	v_mul_f32_e32 v103, 0xbfb8aa3b, v77
	v_exp_f32_e32 v102, v102
	v_exp_f32_e32 v103, v103
	v_pk_add_f32 v[98:99], v[98:99], 1.0 op_sel_hi:[1,0]
	v_rcp_f32_e32 v119, v44
	v_rcp_f32_e32 v120, v45
	v_pk_add_f32 v[100:101], v[100:101], 1.0 op_sel_hi:[1,0]
	v_rcp_f32_e32 v121, v98
	v_rcp_f32_e32 v122, v99
	v_pk_add_f32 v[102:103], v[102:103], 1.0 op_sel_hi:[1,0]
	v_rcp_f32_e32 v123, v100
	v_rcp_f32_e32 v124, v101
	v_rcp_f32_e32 v125, v102
	v_rcp_f32_e32 v126, v103
	v_mul_f32_e32 v41, v46, v119
	s_mov_b64 vcc, s[2:3]
	v_mul_f32_e32 v44, v47, v120
	s_mov_b64 vcc, s[4:5]
	v_mul_f32_e32 v45, v48, v121
	s_mov_b64 vcc, s[6:7]
	v_bfe_u32 v46, v41, 16, 1
	v_mul_f32_e32 v47, v49, v122
	s_mov_b64 vcc, s[8:9]
	v_bfe_u32 v48, v44, 16, 1
	v_add3_u32 v41, v41, v46, s30
	v_mov_b32_e32 v46, v47
	v_mul_f32_e32 v47, v64, v123
	s_mov_b64 vcc, s[10:11]
	v_add3_u32 v44, v44, v48, s30
	v_mul_f32_e32 v48, v65, v124
	s_mov_b64 vcc, s[12:13]
	v_bfe_u32 v49, v45, 16, 1
	v_bfe_u32 v64, v46, 16, 1
	v_perm_b32 v240, v44, v41, s31
	v_mov_b32_e32 v41, v48
	v_mul_f32_e32 v48, v76, v125
	s_mov_b64 vcc, s[14:15]
	v_add3_u32 v45, v45, v49, s30
	v_bfe_u32 v49, v47, 16, 1
	v_add3_u32 v46, v46, v64, s30
	v_mul_f32_e32 v64, v77, v126
	v_bfe_u32 v65, v41, 16, 1
	v_add3_u32 v47, v47, v49, s30
	v_mov_b32_e32 v49, v64
	v_perm_b32 v241, v46, v45, s31
	v_bfe_u32 v46, v48, 16, 1
	v_add3_u32 v41, v41, v65, s30
	v_bfe_u32 v64, v49, 16, 1
	v_add3_u32 v48, v48, v46, s30
	v_perm_b32 v242, v41, v47, s31
	v_add3_u32 v41, v49, v64, s30
	v_perm_b32 v243, v41, v48, s31
	global_store_dwordx4 v[172:173], v[240:243], off
	v_pk_fma_f32 v[50:51], v[16:17], v[70:71], v[50:51]
	v_pk_fma_f32 v[54:55], v[4:5], v[70:71], v[54:55]
	v_pk_fma_f32 v[70:71], v[0:1], v[70:71], v[32:33]
	v_pk_fma_f32 v[74:75], v[18:19], v[82:83], v[74:75]
	v_pk_fma_f32 v[72:73], v[6:7], v[82:83], v[72:73]
	v_pk_fma_f32 v[82:83], v[2:3], v[82:83], v[34:35]
	v_pk_fma_f32 v[78:79], v[26:27], v[90:91], v[78:79]
	v_pk_fma_f32 v[80:81], v[14:15], v[90:91], v[80:81]
	v_pk_fma_f32 v[90:91], v[10:11], v[90:91], v[38:39]
	v_and_b32_e32 v49, 0xffff0000, v212
	v_lshlrev_b32_e32 v48, 16, v212
	v_pk_fma_f32 v[50:51], v[20:21], v[48:49], v[50:51]
	v_and_b32_e32 v65, 0xffff0000, v213
	v_lshlrev_b32_e32 v64, 16, v213
	v_pk_fma_f32 v[54:55], v[16:17], v[48:49], v[54:55]
	v_pk_fma_f32 v[70:71], v[4:5], v[48:49], v[70:71]
	v_mul_f32_e32 v41, 0xbfb8aa3b, v50
	v_mul_f32_e32 v49, 0xbfb8aa3b, v51
	v_pk_fma_f32 v[74:75], v[22:23], v[64:65], v[74:75]
	v_exp_f32_e32 v48, v41
	v_exp_f32_e32 v49, v49
	v_and_b32_e32 v69, 0xffff0000, v214
	v_lshlrev_b32_e32 v68, 16, v214
	v_pk_fma_f32 v[72:73], v[18:19], v[64:65], v[72:73]
	v_pk_fma_f32 v[64:65], v[6:7], v[64:65], v[82:83]
	v_mul_f32_e32 v82, 0xbfb8aa3b, v74
	v_mul_f32_e32 v83, 0xbfb8aa3b, v75
	v_and_b32_e32 v77, 0xffff0000, v215
	v_lshlrev_b32_e32 v76, 16, v215
	v_pk_fma_f32 v[84:85], v[28:29], v[68:69], v[92:93]
	v_exp_f32_e32 v82, v82
	v_exp_f32_e32 v83, v83
	v_pk_fma_f32 v[78:79], v[30:31], v[76:77], v[78:79]
	v_pk_fma_f32 v[80:81], v[26:27], v[76:77], v[80:81]
	v_pk_fma_f32 v[76:77], v[14:15], v[76:77], v[90:91]
	v_mul_f32_e32 v90, 0xbfb8aa3b, v84
	v_mul_f32_e32 v91, 0xbfb8aa3b, v85
	v_exp_f32_e32 v90, v90
	v_exp_f32_e32 v91, v91
	v_pk_add_f32 v[48:49], v[48:49], 1.0 op_sel_hi:[1,0]
	v_pk_fma_f32 v[92:93], v[24:25], v[68:69], v[94:95]
	v_mul_f32_e32 v94, 0xbfb8aa3b, v78
	v_mul_f32_e32 v95, 0xbfb8aa3b, v79
	v_pk_fma_f32 v[68:69], v[12:13], v[68:69], v[96:97]
	v_exp_f32_e32 v94, v94
	v_exp_f32_e32 v95, v95
	v_pk_add_f32 v[82:83], v[82:83], 1.0 op_sel_hi:[1,0]
	v_rcp_f32_e32 v111, v48
	v_rcp_f32_e32 v112, v49
	v_pk_add_f32 v[90:91], v[90:91], 1.0 op_sel_hi:[1,0]
	v_rcp_f32_e32 v113, v82
	v_rcp_f32_e32 v114, v83
	v_pk_add_f32 v[94:95], v[94:95], 1.0 op_sel_hi:[1,0]
	v_rcp_f32_e32 v115, v90
	v_rcp_f32_e32 v116, v91
	v_rcp_f32_e32 v117, v94
	v_rcp_f32_e32 v118, v95
	v_mul_f32_e32 v41, v50, v111
	s_mov_b64 vcc, s[2:3]
	v_mul_f32_e32 v48, v51, v112
	s_mov_b64 vcc, s[4:5]
	v_mul_f32_e32 v49, v74, v113
	s_mov_b64 vcc, s[6:7]
	v_bfe_u32 v50, v41, 16, 1
	v_mul_f32_e32 v51, v75, v114
	s_mov_b64 vcc, s[8:9]
	v_bfe_u32 v74, v48, 16, 1
	v_add3_u32 v41, v41, v50, s30
	v_mov_b32_e32 v50, v51
	v_mul_f32_e32 v51, v84, v115
	s_mov_b64 vcc, s[10:11]
	v_add3_u32 v48, v48, v74, s30
	v_mul_f32_e32 v74, v85, v116
	s_mov_b64 vcc, s[12:13]
	v_bfe_u32 v75, v49, 16, 1
	v_perm_b32 v244, v48, v41, s31
	v_mov_b32_e32 v41, v74
	v_mul_f32_e32 v74, v78, v117
	s_mov_b64 vcc, s[14:15]
	v_bfe_u32 v82, v50, 16, 1
	v_add3_u32 v49, v49, v75, s30
	v_bfe_u32 v75, v51, 16, 1
	v_mul_f32_e32 v78, v79, v118
	v_add3_u32 v50, v50, v82, s30
	v_bfe_u32 v82, v41, 16, 1
	v_add3_u32 v51, v51, v75, s30
	v_mov_b32_e32 v75, v78
	v_perm_b32 v245, v50, v49, s31
; DEVINL u16 f2bf(float f) { uint32_t u = __float_as_uint(f); u += 0x7FFFu + ((u >> 16) & 1u); return (u16)(u >> 16); }
; DEVINL float bfs2f(short h) { return __uint_as_float(((uint32_t)(u16)h) << 16); }
; DEVINL void phase_conv(const Params& p, int layer, int wv) {
;     ...
;     for (int run = blockIdx.x * 2 + half; run < T_TOK / 32; run += gridDim.x * 2) {
;       const int tokA = run * 32;
;       const int l0 = tokA & 4095;
;       const u16* src = hb + (size_t)tokA * HS + 1024 + ch0;
;       bf16x8 r0, r1, r2;
;       const bf16x8 zero8 = {0, 0, 0, 0, 0, 0, 0, 0};
;       r0 = (l0 >= 3) ? *(const bf16x8*)(src - 3 * (long)HS) : zero8;
;       r1 = (l0 >= 2) ? *(const bf16x8*)(src - 2 * (long)HS) : zero8;
;       r2 = (l0 >= 1) ? *(const bf16x8*)(src - 1 * (long)HS) : zero8;
; #pragma unroll 8
;       for (int i = 0; i < 32; ++i) {
;         const bf16x8 r3 = *(const bf16x8*)(src + (size_t)i * HS);
;         bf16x8 o;
; #pragma unroll
;         for (int e = 0; e < 8; ++e) {
;           float v = bias[e] + w[0][e] * bfs2f(r0[e]) + w[1][e] * bfs2f(r1[e]) + w[2][e] * bfs2f(r2[e]) + w[3][e] * bfs2f(r3[e]);
;           v = v / (1.f + __expf(-v));
;           o[e] = (short)f2bf(v);
;         }
;         *(bf16x8*)(xc + (size_t)(tokA + i) * 1536 + ch0) = o;
;         r0 = r1; r1 = r2; r2 = r3;
;       }
	v_bfe_u32 v50, v74, 16, 1
	v_add3_u32 v41, v41, v82, s30
	v_bfe_u32 v78, v75, 16, 1
	v_add3_u32 v74, v74, v50, s30
	v_perm_b32 v246, v41, v51, s31
	v_add3_u32 v41, v75, v78, s30
	v_perm_b32 v247, v41, v74, s31
	global_store_dwordx4 v[174:175], v[244:247], off
	v_and_b32_e32 v67, 0xffff0000, v216
	v_lshlrev_b32_e32 v66, 16, v216
	v_and_b32_e32 v75, 0xffff0000, v217
	v_lshlrev_b32_e32 v74, 16, v217
	v_pk_fma_f32 v[54:55], v[20:21], v[66:67], v[54:55]
	v_pk_fma_f32 v[72:73], v[22:23], v[74:75], v[72:73]
	v_pk_fma_f32 v[74:75], v[18:19], v[74:75], v[64:65]
	v_mul_f32_e32 v41, 0xbfb8aa3b, v54
	v_mul_f32_e32 v65, 0xbfb8aa3b, v55
	v_exp_f32_e32 v64, v41
	v_exp_f32_e32 v65, v65
	v_and_b32_e32 v79, 0xffff0000, v218
	v_lshlrev_b32_e32 v78, 16, v218
	v_pk_fma_f32 v[70:71], v[16:17], v[66:67], v[70:71]
	v_mul_f32_e32 v66, 0xbfb8aa3b, v72
	v_mul_f32_e32 v67, 0xbfb8aa3b, v73
	v_pk_fma_f32 v[84:85], v[28:29], v[78:79], v[92:93]
	v_exp_f32_e32 v66, v66
	v_exp_f32_e32 v67, v67
	v_and_b32_e32 v83, 0xffff0000, v219
	v_lshlrev_b32_e32 v82, 16, v219
	v_pk_fma_f32 v[68:69], v[24:25], v[78:79], v[68:69]
	v_mul_f32_e32 v78, 0xbfb8aa3b, v84
	v_mul_f32_e32 v79, 0xbfb8aa3b, v85
	v_pk_fma_f32 v[80:81], v[30:31], v[82:83], v[80:81]
	v_exp_f32_e32 v78, v78
	v_exp_f32_e32 v79, v79
	v_pk_add_f32 v[64:65], v[64:65], 1.0 op_sel_hi:[1,0]
	v_pk_fma_f32 v[76:77], v[26:27], v[82:83], v[76:77]
	v_mul_f32_e32 v82, 0xbfb8aa3b, v80
	v_mul_f32_e32 v83, 0xbfb8aa3b, v81
	v_exp_f32_e32 v82, v82
	v_exp_f32_e32 v83, v83
	v_pk_add_f32 v[66:67], v[66:67], 1.0 op_sel_hi:[1,0]
	v_rcp_f32_e32 v103, v64
	v_rcp_f32_e32 v104, v65
	v_pk_add_f32 v[78:79], v[78:79], 1.0 op_sel_hi:[1,0]
	v_rcp_f32_e32 v105, v66
	v_rcp_f32_e32 v106, v67
	v_pk_add_f32 v[82:83], v[82:83], 1.0 op_sel_hi:[1,0]
	v_rcp_f32_e32 v107, v78
	v_rcp_f32_e32 v108, v79
	v_rcp_f32_e32 v109, v82
	v_rcp_f32_e32 v110, v83
	v_mul_f32_e32 v41, v54, v103
	s_mov_b64 vcc, s[2:3]
	v_mul_f32_e32 v54, v55, v104
	s_mov_b64 vcc, s[4:5]
	v_mul_f32_e32 v55, v72, v105
	s_mov_b64 vcc, s[6:7]
	v_bfe_u32 v64, v41, 16, 1
	v_mul_f32_e32 v65, v73, v106
	s_mov_b64 vcc, s[8:9]
	v_bfe_u32 v66, v54, 16, 1
	v_add3_u32 v41, v41, v64, s30
	v_mul_f32_e32 v64, v84, v107
	s_mov_b64 vcc, s[10:11]
	v_add3_u32 v54, v54, v66, s30
	v_mul_f32_e32 v72, v85, v108
	s_mov_b64 vcc, s[12:13]
	v_bfe_u32 v67, v55, 16, 1
	v_mov_b32_e32 v66, v64
	v_bfe_u32 v73, v65, 16, 1
	v_perm_b32 v248, v54, v41, s31
	v_mul_f32_e32 v54, v80, v109
	s_mov_b64 vcc, s[14:15]
	v_add3_u32 v55, v55, v67, s30
	v_mov_b32_e32 v41, v72
	v_add3_u32 v65, v65, v73, s30
	v_mul_f32_e32 v72, v81, v110
	v_bfe_u32 v67, v66, 16, 1
	v_bfe_u32 v73, v41, 16, 1
	v_perm_b32 v249, v65, v55, s31
	v_mov_b32_e32 v55, v72
	v_add3_u32 v66, v66, v67, s30
	v_bfe_u32 v67, v54, 16, 1
	v_add3_u32 v41, v41, v73, s30
	v_bfe_u32 v72, v55, 16, 1
	v_add3_u32 v54, v54, v67, s30
	v_perm_b32 v250, v41, v66, s31
	v_add3_u32 v41, v55, v72, s30
	v_perm_b32 v251, v41, v54, s31
	global_store_dwordx4 v[178:179], v[248:251], off
	v_lshl_add_u64 v[42:43], v[42:43], 0, s[22:23]
	v_and_b32_e32 v65, 0xffff0000, v220
	v_lshlrev_b32_e32 v64, 16, v220
	v_and_b32_e32 v73, 0xffff0000, v222
	v_lshlrev_b32_e32 v72, 16, v222
	v_pk_fma_f32 v[64:65], v[20:21], v[64:65], v[70:71]
	v_and_b32_e32 v67, 0xffff0000, v221
	v_lshlrev_b32_e32 v66, 16, v221
	v_pk_fma_f32 v[68:69], v[28:29], v[72:73], v[68:69]
	v_mul_f32_e32 v41, 0xbfb8aa3b, v64
	v_mul_f32_e32 v73, 0xbfb8aa3b, v65
	v_pk_fma_f32 v[66:67], v[22:23], v[66:67], v[74:75]
	v_exp_f32_e32 v72, v41
	v_exp_f32_e32 v73, v73
	v_mul_f32_e32 v74, 0xbfb8aa3b, v66
	v_mul_f32_e32 v75, 0xbfb8aa3b, v67
	v_and_b32_e32 v79, 0xffff0000, v223
	v_lshlrev_b32_e32 v78, 16, v223
	v_exp_f32_e32 v74, v74
	v_exp_f32_e32 v75, v75
	v_pk_fma_f32 v[70:71], v[30:31], v[78:79], v[76:77]
	v_mul_f32_e32 v76, 0xbfb8aa3b, v68
	v_mul_f32_e32 v77, 0xbfb8aa3b, v69
	v_exp_f32_e32 v76, v76
	v_exp_f32_e32 v77, v77
	v_pk_add_f32 v[72:73], v[72:73], 1.0 op_sel_hi:[1,0]
	v_mul_f32_e32 v78, 0xbfb8aa3b, v70
	v_mul_f32_e32 v79, 0xbfb8aa3b, v71
	v_exp_f32_e32 v78, v78
	v_exp_f32_e32 v79, v79
	v_pk_add_f32 v[74:75], v[74:75], 1.0 op_sel_hi:[1,0]
	v_rcp_f32_e32 v97, v72
	v_rcp_f32_e32 v98, v73
	v_pk_add_f32 v[76:77], v[76:77], 1.0 op_sel_hi:[1,0]
	v_rcp_f32_e32 v99, v74
	v_rcp_f32_e32 v100, v75
	v_pk_add_f32 v[78:79], v[78:79], 1.0 op_sel_hi:[1,0]
	v_rcp_f32_e32 v101, v76
	v_rcp_f32_e32 v102, v77
	v_rcp_f32_e32 v103, v78
	v_rcp_f32_e32 v104, v79
	v_mul_f32_e32 v41, v64, v97
	s_mov_b64 vcc, s[2:3]
	v_mul_f32_e32 v64, v65, v98
	s_mov_b64 vcc, s[4:5]
	v_mul_f32_e32 v65, v66, v99
	s_mov_b64 vcc, s[6:7]
	v_mul_f32_e32 v66, v67, v100
	s_mov_b64 vcc, s[8:9]
	v_bfe_u32 v72, v41, 16, 1
	v_bfe_u32 v73, v64, 16, 1
	v_mul_f32_e32 v67, v68, v101
	s_mov_b64 vcc, s[10:11]
	v_add3_u32 v41, v41, v72, s30
	v_add3_u32 v64, v64, v73, s30
	v_mul_f32_e32 v68, v69, v102
	s_mov_b64 vcc, s[12:13]
	v_perm_b32 v160, v64, v41, s31
	v_mov_b32_e32 v41, v68
	v_mul_f32_e32 v68, v70, v103
	s_mov_b64 vcc, s[14:15]
	v_bfe_u32 v72, v65, 16, 1
	v_bfe_u32 v73, v66, 16, 1
	v_bfe_u32 v69, v67, 16, 1
	v_mul_f32_e32 v70, v71, v104
	v_add3_u32 v65, v65, v72, s30
	v_add3_u32 v66, v66, v73, s30
	v_bfe_u32 v72, v41, 16, 1
	v_add3_u32 v67, v67, v69, s30
	v_mov_b32_e32 v69, v70
	v_perm_b32 v161, v66, v65, s31
	v_bfe_u32 v66, v68, 16, 1
	v_add3_u32 v41, v41, v72, s30
	v_bfe_u32 v70, v69, 16, 1
	v_add3_u32 v68, v68, v66, s30
	v_perm_b32 v162, v41, v67, s31
	v_add3_u32 v41, v69, v70, s30
	v_perm_b32 v163, v41, v68, s31
	global_store_dwordx4 v[180:181], v[160:163], off
	s_cbranch_scc0 .LBB0_1477
	v_add_u32_e32 v88, s24, v88
	v_cmp_lt_i32_e32 vcc, s37, v88
	s_or_b64 s[18:19], vcc, s[18:19]
	v_add_u32_e32 v89, s25, v89
	s_andn2_b64 exec, exec, s[18:19]
	s_cbranch_execnz .LBB0_1470
